# v51 + mid-step LDS-DMA (two k-steps in flight, prologue issues first two) in the three merge k-loops
# baseline (speedup 1.0000x reference)
.LBB0_83:
	s_lshl_b32 s8, s34, 3
	s_mul_i32 s9, s8, s2
	s_cmpk_gt_i32 s9, 0x33f
	s_mov_b32 s35, 2
	s_mov_b64 s[40:41], 0x10000
	s_cbranch_scc1 .LBB0_92
	s_or_b32 s8, s8, s14
	s_mul_i32 s8, s8, s2
	s_add_i32 s8, s8, s15
	s_cmpk_gt_i32 s8, 0x33f
	s_mov_b32 s35, 4
	s_cbranch_scc1 .LBB0_92
	s_mul_hi_i32 s9, s8, 0x4ec4ec4f
	s_lshr_b32 s10, s9, 31
	s_ashr_i32 s9, s9, 8
	s_add_i32 s9, s9, s10
	s_lshl_b32 s10, s9, 3
	s_mulk_i32 s9, 0x340
	s_sub_i32 s8, s8, s9
	s_ashr_i32 s36, s8, 3
	s_and_b32 s9, s8, 7
	s_mul_i32 s12, s36, 0x1f4000
	s_or_b32 s10, s10, s9
	s_ashr_i32 s13, s12, 31
	s_add_u32 s38, s0, s12
	s_addc_u32 s39, s1, s13
	s_ashr_i32 s11, s10, 31
	s_lshl_b64 s[8:9], s[10:11], 18
	v_lshl_add_u64 v[102:103], s[38:39], 0, v[82:83]
	v_lshlrev_b32_e32 v96, 1, v80
	v_readfirstlane_b32 s11, v81
	v_add_u32_e32 v133, 0x1000, v81
	v_lshl_add_u64 v[104:105], v[102:103], 0, v[96:97]
	s_mov_b32 m0, s11
	s_mov_b64 s[38:39], 0x64000
	v_readfirstlane_b32 s11, v133
	v_add_u32_e32 v132, 0x2000, v81
	global_load_lds_dwordx4 v[104:105], off
	v_lshl_add_u64 v[0:1], v[104:105], 0, s[38:39]
	s_mov_b32 m0, s11
	s_mov_b64 s[38:39], 0xc8000
	v_readfirstlane_b32 s11, v132
	v_add_u32_e32 v131, 0x3000, v81
	global_load_lds_dwordx4 v[0:1], off
	v_lshl_add_u64 v[0:1], v[104:105], 0, s[38:39]
	s_mov_b32 m0, s11
	s_mov_b64 s[38:39], 0x12c000
	v_readfirstlane_b32 s11, v131
	v_add_u32_e32 v130, 0x4000, v81
	global_load_lds_dwordx4 v[0:1], off
	v_lshl_add_u64 v[0:1], v[104:105], 0, s[38:39]
	s_mov_b32 m0, s11
	s_mov_b64 s[38:39], 0x190000
	v_readfirstlane_b32 s11, v130
	v_add_u32_e32 v129, 0x5000, v81
	global_load_lds_dwordx4 v[0:1], off
	v_lshl_add_u64 v[0:1], v[104:105], 0, s[38:39]
	s_mov_b32 m0, s11
	v_readfirstlane_b32 s11, v129
	v_add_u32_e32 v128, 0x6000, v81
	global_load_lds_dwordx4 v[0:1], off
	v_lshl_add_u64 v[0:1], v[84:85], 0, s[8:9]
	s_mov_b32 m0, s11
	v_readfirstlane_b32 s11, v128
	v_add_u32_e32 v127, 0x7000, v81
	global_load_lds_dwordx4 v[0:1], off
	v_lshl_add_u64 v[2:3], v[0:1], 0, s[40:41]
	s_mov_b32 m0, s11
	s_mov_b64 s[38:39], 0x20000
	v_readfirstlane_b32 s11, v127
	v_add_u32_e32 v126, 0x8000, v81
	global_load_lds_dwordx4 v[2:3], off
	v_lshl_add_u64 v[2:3], v[0:1], 0, s[38:39]
	s_mov_b32 m0, s11
	s_mov_b64 s[38:39], 0x30000
	v_readfirstlane_b32 s11, v126
	global_load_lds_dwordx4 v[2:3], off
	v_lshl_add_u64 v[0:1], v[0:1], 0, s[38:39]
	s_mov_b32 m0, s11
	v_lshl_add_u64 v[94:95], v[90:91], 0, s[12:13]
	global_load_lds_dwordx4 v[0:1], off
	s_nop 0
	v_mov_b32_e32 v0, 0
	v_lshl_add_u64 v[100:101], v[92:93], 0, s[8:9]
	s_mov_b32 s11, 0
	s_mov_b64 s[12:13], 0
	v_mov_b32_e32 v1, v0
	v_mov_b32_e32 v2, v0
	v_mov_b32_e32 v3, v0
	v_mov_b32_e32 v4, v0
	v_mov_b32_e32 v5, v0
	v_mov_b32_e32 v6, v0
	v_mov_b32_e32 v7, v0
	v_mov_b32_e32 v8, v0
	v_mov_b32_e32 v9, v0
	v_mov_b32_e32 v10, v0
	v_mov_b32_e32 v11, v0
	v_mov_b32_e32 v12, v0
	v_mov_b32_e32 v13, v0
	v_mov_b32_e32 v14, v0
	v_mov_b32_e32 v15, v0
	v_mov_b32_e32 v16, v0
	v_mov_b32_e32 v17, v0
	v_mov_b32_e32 v18, v0
	v_mov_b32_e32 v19, v0
	v_mov_b32_e32 v20, v0
	v_mov_b32_e32 v21, v0
	v_mov_b32_e32 v22, v0
	v_mov_b32_e32 v23, v0
	v_mov_b32_e32 v24, v0
	v_mov_b32_e32 v25, v0
	v_mov_b32_e32 v26, v0
	v_mov_b32_e32 v27, v0
	v_mov_b32_e32 v28, v0
	v_mov_b32_e32 v29, v0
	v_mov_b32_e32 v30, v0
	v_mov_b32_e32 v31, v0
	v_mov_b32_e32 v32, v0
	v_mov_b32_e32 v33, v0
	v_mov_b32_e32 v34, v0
	v_mov_b32_e32 v35, v0
	v_mov_b32_e32 v36, v0
	v_mov_b32_e32 v37, v0
	v_mov_b32_e32 v38, v0
	v_mov_b32_e32 v39, v0
	v_mov_b32_e32 v40, v0
	v_mov_b32_e32 v41, v0
	v_mov_b32_e32 v42, v0
	v_mov_b32_e32 v43, v0
	v_mov_b32_e32 v44, v0
	v_mov_b32_e32 v45, v0
	v_mov_b32_e32 v46, v0
	v_mov_b32_e32 v47, v0
	v_mov_b32_e32 v48, v0
	v_mov_b32_e32 v49, v0
	v_mov_b32_e32 v50, v0
	v_mov_b32_e32 v51, v0
	v_mov_b32_e32 v52, v0
	v_mov_b32_e32 v53, v0
	v_mov_b32_e32 v54, v0
	v_mov_b32_e32 v55, v0
	v_mov_b32_e32 v56, v0
	v_mov_b32_e32 v57, v0
	v_mov_b32_e32 v58, v0
	v_mov_b32_e32 v59, v0
	v_mov_b32_e32 v60, v0
	v_mov_b32_e32 v61, v0
	v_mov_b32_e32 v62, v0
	v_mov_b32_e32 v63, v0
	v_mov_b32_e32 v64, v0
	v_mov_b32_e32 v65, v0
	v_mov_b32_e32 v66, v0
	v_mov_b32_e32 v67, v0
	v_mov_b32_e32 v68, v0
	v_mov_b32_e32 v69, v0
	v_mov_b32_e32 v70, v0
	v_mov_b32_e32 v71, v0
	v_mov_b32_e32 v72, v0
	v_mov_b32_e32 v73, v0
	v_mov_b32_e32 v74, v0
	v_mov_b32_e32 v75, v0
	v_mov_b32_e32 v76, v0
	v_mov_b32_e32 v77, v0
	v_mov_b32_e32 v78, v0
	v_mov_b32_e32 v79, v0
	s_nop 0
	s_nop 0
	s_mov_b32 s37, 0x9000
	v_add_u32_e32 v204, s37, v81
	v_lshl_add_u64 v[202:203], v[94:95], 0, s[12:13]
	s_mov_b64 s[38:39], 0x6181080
	v_readfirstlane_b32 s37, v204
	v_add_u32_e32 v228, 0x1000, v204
	v_lshl_add_u64 v[210:211], v[202:203], 0, s[38:39]
	s_mov_b32 m0, s37
	s_mov_b64 s[38:39], 0x61e5080
	v_readfirstlane_b32 s37, v228
	v_add_u32_e32 v228, 0x2000, v204
	global_load_lds_dwordx4 v[210:211], off
	v_lshl_add_u64 v[210:211], v[202:203], 0, s[38:39]
	s_mov_b32 m0, s37
	s_mov_b64 s[38:39], 0x6249080
	v_readfirstlane_b32 s37, v228
	v_add_u32_e32 v228, 0x3000, v204
	global_load_lds_dwordx4 v[210:211], off
	v_lshl_add_u64 v[210:211], v[202:203], 0, s[38:39]
	s_mov_b32 m0, s37
	s_mov_b64 s[38:39], 0x62ad080
	v_readfirstlane_b32 s37, v228
	global_load_lds_dwordx4 v[210:211], off
	v_lshl_add_u64 v[210:211], v[202:203], 0, s[38:39]
	s_mov_b32 m0, s37
	s_mov_b64 s[38:39], 0x6311080
	global_load_lds_dwordx4 v[210:211], off
	v_add_u32_e32 v210, 0x4000, v204
	v_lshl_add_u64 v[202:203], v[202:203], 0, s[38:39]
	v_readfirstlane_b32 s37, v210
	s_mov_b32 m0, s37
	v_add_u32_e32 v228, 0x5000, v204
	global_load_lds_dwordx4 v[202:203], off
	v_lshl_add_u64 v[202:203], v[100:101], 0, s[12:13]
	s_mov_b64 s[38:39], 0x14531080
	v_readfirstlane_b32 s37, v228
	v_add_u32_e32 v228, 0x6000, v204
	v_lshl_add_u64 v[210:211], v[202:203], 0, s[38:39]
	s_mov_b32 m0, s37
	s_mov_b64 s[38:39], 0x14541080
	v_readfirstlane_b32 s37, v228
	v_add_u32_e32 v228, 0x7000, v204
	global_load_lds_dwordx4 v[210:211], off
	v_lshl_add_u64 v[210:211], v[202:203], 0, s[38:39]
	s_mov_b32 m0, s37
	s_mov_b64 s[38:39], 0x14551080
	v_readfirstlane_b32 s37, v228
	global_load_lds_dwordx4 v[210:211], off
	v_lshl_add_u64 v[210:211], v[202:203], 0, s[38:39]
	s_mov_b32 m0, s37
	s_mov_b64 s[38:39], 0x14561080
	global_load_lds_dwordx4 v[210:211], off
	v_add_u32_e32 v210, 0x8000, v204
	v_lshl_add_u64 v[202:203], v[202:203], 0, s[38:39]
	v_readfirstlane_b32 s37, v210
	s_mov_b32 m0, s37
	s_nop 0
	global_load_lds_dwordx4 v[202:203], off
	s_waitcnt vmcnt(9) lgkmcnt(0)
	s_barrier
.LBB0_86:
	s_add_i32 s35, s11, 1
	s_bitcmp1_b32 s11, 0
	s_cselect_b32 s11, 0x9000, 0
	s_add_i32 s11, s11, 0
	v_add_u32_e32 v114, s11, v116
	v_add_u32_e32 v115, v114, v117
	ds_read_b128 v[106:109], v115
	ds_read_b128 v[110:113], v115 offset:2048
	ds_read_b128 v[122:125], v115 offset:4096
	ds_read_b128 v[156:159], v115 offset:6144
	v_add_u32_e32 v114, v114, v118
	ds_read_b128 v[166:169], v115 offset:8192
	ds_read_b128 v[178:181], v114 offset:20480
	ds_read_b128 v[182:185], v114 offset:22528
	ds_read_b128 v[186:189], v114 offset:24576
	ds_read_b128 v[190:193], v114 offset:26624
	v_add_u32_e32 v210, s11, v119
	v_add_u32_e32 v211, v210, v117
	ds_read_b128 v[212:215], v211
	ds_read_b128 v[216:219], v211 offset:2048
	ds_read_b128 v[220:223], v211 offset:4096
	ds_read_b128 v[224:227], v211 offset:6144
	v_add_u32_e32 v228, v210, v118
	ds_read_b128 v[230:233], v211 offset:8192
	ds_read_b128 v[234:237], v228 offset:20480
	ds_read_b128 v[238:241], v228 offset:22528
	ds_read_b128 v[242:245], v228 offset:24576
	ds_read_b128 v[246:249], v228 offset:26624
	s_setprio 1
	s_waitcnt lgkmcnt(9)
	v_mfma_f32_16x16x32_bf16 v[76:79], v[178:181], v[106:109], v[76:79]
	v_mfma_f32_16x16x32_bf16 v[72:75], v[182:185], v[106:109], v[72:75]
	v_mfma_f32_16x16x32_bf16 v[68:71], v[186:189], v[106:109], v[68:71]
	v_mfma_f32_16x16x32_bf16 v[64:67], v[190:193], v[106:109], v[64:67]
	v_mfma_f32_16x16x32_bf16 v[60:63], v[178:181], v[110:113], v[60:63]
	v_mfma_f32_16x16x32_bf16 v[56:59], v[182:185], v[110:113], v[56:59]
	v_mfma_f32_16x16x32_bf16 v[52:55], v[186:189], v[110:113], v[52:55]
	v_mfma_f32_16x16x32_bf16 v[48:51], v[190:193], v[110:113], v[48:51]
	v_mfma_f32_16x16x32_bf16 v[44:47], v[178:181], v[122:125], v[44:47]
	v_mfma_f32_16x16x32_bf16 v[40:43], v[182:185], v[122:125], v[40:43]
	v_mfma_f32_16x16x32_bf16 v[36:39], v[186:189], v[122:125], v[36:39]
	v_mfma_f32_16x16x32_bf16 v[32:35], v[190:193], v[122:125], v[32:35]
	v_mfma_f32_16x16x32_bf16 v[28:31], v[178:181], v[156:159], v[28:31]
	v_mfma_f32_16x16x32_bf16 v[24:27], v[182:185], v[156:159], v[24:27]
	v_mfma_f32_16x16x32_bf16 v[20:23], v[186:189], v[156:159], v[20:23]
	v_mfma_f32_16x16x32_bf16 v[16:19], v[190:193], v[156:159], v[16:19]
	v_mfma_f32_16x16x32_bf16 v[12:15], v[178:181], v[166:169], v[12:15]
	v_mfma_f32_16x16x32_bf16 v[8:11], v[182:185], v[166:169], v[8:11]
	v_mfma_f32_16x16x32_bf16 v[4:7], v[186:189], v[166:169], v[4:7]
	v_mfma_f32_16x16x32_bf16 v[0:3], v[190:193], v[166:169], v[0:3]
	s_setprio 0
	s_setprio 1
	s_waitcnt lgkmcnt(0)
	s_setprio 0
	s_barrier
	s_add_u32 s12, s12, 0x80
	s_addc_u32 s13, s13, 0
	s_mov_b32 s37, s11
	v_add_u32_e32 v204, s37, v81
	v_lshl_add_u64 v[202:203], v[94:95], 0, s[12:13]
	s_mov_b64 s[38:39], 0x6181080
	v_readfirstlane_b32 s37, v204
	v_add_u32_e32 v228, 0x1000, v204
	v_lshl_add_u64 v[210:211], v[202:203], 0, s[38:39]
	s_mov_b32 m0, s37
	s_mov_b64 s[38:39], 0x61e5080
	v_readfirstlane_b32 s37, v228
	v_add_u32_e32 v228, 0x2000, v204
	global_load_lds_dwordx4 v[210:211], off
	v_lshl_add_u64 v[210:211], v[202:203], 0, s[38:39]
	s_mov_b32 m0, s37
	s_mov_b64 s[38:39], 0x6249080
	v_readfirstlane_b32 s37, v228
	v_add_u32_e32 v228, 0x3000, v204
	global_load_lds_dwordx4 v[210:211], off
	v_lshl_add_u64 v[210:211], v[202:203], 0, s[38:39]
	s_mov_b32 m0, s37
	s_mov_b64 s[38:39], 0x62ad080
	v_readfirstlane_b32 s37, v228
	global_load_lds_dwordx4 v[210:211], off
	v_lshl_add_u64 v[210:211], v[202:203], 0, s[38:39]
	s_mov_b32 m0, s37
	s_mov_b64 s[38:39], 0x6311080
	global_load_lds_dwordx4 v[210:211], off
	v_add_u32_e32 v210, 0x4000, v204
	v_lshl_add_u64 v[202:203], v[202:203], 0, s[38:39]
	v_readfirstlane_b32 s37, v210
	s_mov_b32 m0, s37
	v_add_u32_e32 v228, 0x5000, v204
	global_load_lds_dwordx4 v[202:203], off
	v_lshl_add_u64 v[202:203], v[100:101], 0, s[12:13]
	s_mov_b64 s[38:39], 0x14531080
	v_readfirstlane_b32 s37, v228
	v_add_u32_e32 v228, 0x6000, v204
	v_lshl_add_u64 v[210:211], v[202:203], 0, s[38:39]
	s_mov_b32 m0, s37
	s_mov_b64 s[38:39], 0x14541080
	v_readfirstlane_b32 s37, v228
	v_add_u32_e32 v228, 0x7000, v204
	global_load_lds_dwordx4 v[210:211], off
	v_lshl_add_u64 v[210:211], v[202:203], 0, s[38:39]
	s_mov_b32 m0, s37
	s_mov_b64 s[38:39], 0x14551080
	v_readfirstlane_b32 s37, v228
	global_load_lds_dwordx4 v[210:211], off
	v_lshl_add_u64 v[210:211], v[202:203], 0, s[38:39]
	s_mov_b32 m0, s37
	s_mov_b64 s[38:39], 0x14561080
	global_load_lds_dwordx4 v[210:211], off
	v_add_u32_e32 v210, 0x8000, v204
	v_lshl_add_u64 v[202:203], v[202:203], 0, s[38:39]
	v_readfirstlane_b32 s37, v210
	s_mov_b32 m0, s37
	s_nop 0
	global_load_lds_dwordx4 v[202:203], off
	s_setprio 1
	v_mfma_f32_16x16x32_bf16 v[76:79], v[234:237], v[212:215], v[76:79]
	v_mfma_f32_16x16x32_bf16 v[72:75], v[238:241], v[212:215], v[72:75]
	v_mfma_f32_16x16x32_bf16 v[68:71], v[242:245], v[212:215], v[68:71]
	v_mfma_f32_16x16x32_bf16 v[64:67], v[246:249], v[212:215], v[64:67]
	v_mfma_f32_16x16x32_bf16 v[60:63], v[234:237], v[216:219], v[60:63]
	v_mfma_f32_16x16x32_bf16 v[56:59], v[238:241], v[216:219], v[56:59]
	v_mfma_f32_16x16x32_bf16 v[52:55], v[242:245], v[216:219], v[52:55]
	v_mfma_f32_16x16x32_bf16 v[48:51], v[246:249], v[216:219], v[48:51]
	v_mfma_f32_16x16x32_bf16 v[44:47], v[234:237], v[220:223], v[44:47]
	v_mfma_f32_16x16x32_bf16 v[40:43], v[238:241], v[220:223], v[40:43]
	v_mfma_f32_16x16x32_bf16 v[36:39], v[242:245], v[220:223], v[36:39]
	v_mfma_f32_16x16x32_bf16 v[32:35], v[246:249], v[220:223], v[32:35]
	v_mfma_f32_16x16x32_bf16 v[28:31], v[234:237], v[224:227], v[28:31]
	v_mfma_f32_16x16x32_bf16 v[24:27], v[238:241], v[224:227], v[24:27]
	v_mfma_f32_16x16x32_bf16 v[20:23], v[242:245], v[224:227], v[20:23]
	v_mfma_f32_16x16x32_bf16 v[16:19], v[246:249], v[224:227], v[16:19]
	v_mfma_f32_16x16x32_bf16 v[12:15], v[234:237], v[230:233], v[12:15]
	v_mfma_f32_16x16x32_bf16 v[8:11], v[238:241], v[230:233], v[8:11]
	v_mfma_f32_16x16x32_bf16 v[4:7], v[242:245], v[230:233], v[4:7]
	v_mfma_f32_16x16x32_bf16 v[0:3], v[246:249], v[230:233], v[0:3]
	s_setprio 0
	s_cmpk_lg_i32 s12, 0x700
	s_mov_b32 s11, s35
	s_waitcnt vmcnt(9)
	s_barrier
	s_cbranch_scc1 .LBB0_86
	s_add_i32 s35, s11, 1
	s_bitcmp1_b32 s11, 0
	s_cselect_b32 s11, 0x9000, 0
	s_add_i32 s11, s11, 0
	v_add_u32_e32 v114, s11, v116
	v_add_u32_e32 v115, v114, v117
	ds_read_b128 v[106:109], v115
	ds_read_b128 v[110:113], v115 offset:2048
	ds_read_b128 v[122:125], v115 offset:4096
	ds_read_b128 v[156:159], v115 offset:6144
	v_add_u32_e32 v114, v114, v118
	ds_read_b128 v[166:169], v115 offset:8192
	ds_read_b128 v[178:181], v114 offset:20480
	ds_read_b128 v[182:185], v114 offset:22528
	ds_read_b128 v[186:189], v114 offset:24576
	ds_read_b128 v[190:193], v114 offset:26624
	v_add_u32_e32 v210, s11, v119
	v_add_u32_e32 v211, v210, v117
	ds_read_b128 v[212:215], v211
	ds_read_b128 v[216:219], v211 offset:2048
	ds_read_b128 v[220:223], v211 offset:4096
	ds_read_b128 v[224:227], v211 offset:6144
	v_add_u32_e32 v228, v210, v118
	ds_read_b128 v[230:233], v211 offset:8192
	ds_read_b128 v[234:237], v228 offset:20480
	ds_read_b128 v[238:241], v228 offset:22528
	ds_read_b128 v[242:245], v228 offset:24576
	ds_read_b128 v[246:249], v228 offset:26624
	s_setprio 1
	s_waitcnt lgkmcnt(9)
	v_mfma_f32_16x16x32_bf16 v[76:79], v[178:181], v[106:109], v[76:79]
	v_mfma_f32_16x16x32_bf16 v[72:75], v[182:185], v[106:109], v[72:75]
	v_mfma_f32_16x16x32_bf16 v[68:71], v[186:189], v[106:109], v[68:71]
	v_mfma_f32_16x16x32_bf16 v[64:67], v[190:193], v[106:109], v[64:67]
	v_mfma_f32_16x16x32_bf16 v[60:63], v[178:181], v[110:113], v[60:63]
	v_mfma_f32_16x16x32_bf16 v[56:59], v[182:185], v[110:113], v[56:59]
	v_mfma_f32_16x16x32_bf16 v[52:55], v[186:189], v[110:113], v[52:55]
	v_mfma_f32_16x16x32_bf16 v[48:51], v[190:193], v[110:113], v[48:51]
	v_mfma_f32_16x16x32_bf16 v[44:47], v[178:181], v[122:125], v[44:47]
	v_mfma_f32_16x16x32_bf16 v[40:43], v[182:185], v[122:125], v[40:43]
	v_mfma_f32_16x16x32_bf16 v[36:39], v[186:189], v[122:125], v[36:39]
	v_mfma_f32_16x16x32_bf16 v[32:35], v[190:193], v[122:125], v[32:35]
	v_mfma_f32_16x16x32_bf16 v[28:31], v[178:181], v[156:159], v[28:31]
	v_mfma_f32_16x16x32_bf16 v[24:27], v[182:185], v[156:159], v[24:27]
	v_mfma_f32_16x16x32_bf16 v[20:23], v[186:189], v[156:159], v[20:23]
	v_mfma_f32_16x16x32_bf16 v[16:19], v[190:193], v[156:159], v[16:19]
	v_mfma_f32_16x16x32_bf16 v[12:15], v[178:181], v[166:169], v[12:15]
	v_mfma_f32_16x16x32_bf16 v[8:11], v[182:185], v[166:169], v[8:11]
	v_mfma_f32_16x16x32_bf16 v[4:7], v[186:189], v[166:169], v[4:7]
	v_mfma_f32_16x16x32_bf16 v[0:3], v[190:193], v[166:169], v[0:3]
	s_setprio 0
	s_setprio 1
	s_waitcnt lgkmcnt(0)
	v_mfma_f32_16x16x32_bf16 v[76:79], v[234:237], v[212:215], v[76:79]
	v_mfma_f32_16x16x32_bf16 v[72:75], v[238:241], v[212:215], v[72:75]
	v_mfma_f32_16x16x32_bf16 v[68:71], v[242:245], v[212:215], v[68:71]
	v_mfma_f32_16x16x32_bf16 v[64:67], v[246:249], v[212:215], v[64:67]
	v_mfma_f32_16x16x32_bf16 v[60:63], v[234:237], v[216:219], v[60:63]
	v_mfma_f32_16x16x32_bf16 v[56:59], v[238:241], v[216:219], v[56:59]
	v_mfma_f32_16x16x32_bf16 v[52:55], v[242:245], v[216:219], v[52:55]
	v_mfma_f32_16x16x32_bf16 v[48:51], v[246:249], v[216:219], v[48:51]
	v_mfma_f32_16x16x32_bf16 v[44:47], v[234:237], v[220:223], v[44:47]
	v_mfma_f32_16x16x32_bf16 v[40:43], v[238:241], v[220:223], v[40:43]
	v_mfma_f32_16x16x32_bf16 v[36:39], v[242:245], v[220:223], v[36:39]
	v_mfma_f32_16x16x32_bf16 v[32:35], v[246:249], v[220:223], v[32:35]
	v_mfma_f32_16x16x32_bf16 v[28:31], v[234:237], v[224:227], v[28:31]
	v_mfma_f32_16x16x32_bf16 v[24:27], v[238:241], v[224:227], v[24:27]
	v_mfma_f32_16x16x32_bf16 v[20:23], v[242:245], v[224:227], v[20:23]
	v_mfma_f32_16x16x32_bf16 v[16:19], v[246:249], v[224:227], v[16:19]
	v_mfma_f32_16x16x32_bf16 v[12:15], v[234:237], v[230:233], v[12:15]
	v_mfma_f32_16x16x32_bf16 v[8:11], v[238:241], v[230:233], v[8:11]
	v_mfma_f32_16x16x32_bf16 v[4:7], v[242:245], v[230:233], v[4:7]
	v_mfma_f32_16x16x32_bf16 v[0:3], v[246:249], v[230:233], v[0:3]
	s_setprio 0
	s_add_u32 s12, s12, 0x80
	s_addc_u32 s13, s13, 0
	s_mov_b32 s11, s35
	s_waitcnt vmcnt(0)
	s_barrier
	v_add_u32_e32 v122, v120, v118
	v_add_u32_e32 v123, v120, v117
	ds_read_b128 v[106:109], v122 offset:63488
	ds_read_b128 v[110:113], v122 offset:61440
	ds_read_b128 v[156:159], v122 offset:59392
	ds_read_b128 v[166:169], v122 offset:57344
	ds_read_b128 v[178:181], v123 offset:45056
	ds_read_b128 v[182:185], v123 offset:43008
	ds_read_b128 v[186:189], v123 offset:40960
	ds_read_b128 v[190:193], v123 offset:38912
	ds_read_b128 v[194:197], v123 offset:36864
	s_setprio 1
	s_waitcnt lgkmcnt(0)
	v_mfma_f32_16x16x32_bf16 v[76:79], v[166:169], v[194:197], v[76:79]
	v_mfma_f32_16x16x32_bf16 v[72:75], v[156:159], v[194:197], v[72:75]
	v_mfma_f32_16x16x32_bf16 v[68:71], v[110:113], v[194:197], v[68:71]
	v_mfma_f32_16x16x32_bf16 v[64:67], v[106:109], v[194:197], v[64:67]
	v_mfma_f32_16x16x32_bf16 v[60:63], v[166:169], v[190:193], v[60:63]
	v_mfma_f32_16x16x32_bf16 v[56:59], v[156:159], v[190:193], v[56:59]
	v_mfma_f32_16x16x32_bf16 v[52:55], v[110:113], v[190:193], v[52:55]
	v_mfma_f32_16x16x32_bf16 v[48:51], v[106:109], v[190:193], v[48:51]
	v_mfma_f32_16x16x32_bf16 v[44:47], v[166:169], v[186:189], v[44:47]
	v_mfma_f32_16x16x32_bf16 v[40:43], v[156:159], v[186:189], v[40:43]
	v_mfma_f32_16x16x32_bf16 v[36:39], v[110:113], v[186:189], v[36:39]
	v_mfma_f32_16x16x32_bf16 v[32:35], v[106:109], v[186:189], v[32:35]
	v_mfma_f32_16x16x32_bf16 v[28:31], v[166:169], v[182:185], v[28:31]
	v_mfma_f32_16x16x32_bf16 v[24:27], v[156:159], v[182:185], v[24:27]
	v_mfma_f32_16x16x32_bf16 v[20:23], v[110:113], v[182:185], v[20:23]
	v_mfma_f32_16x16x32_bf16 v[16:19], v[106:109], v[182:185], v[16:19]
	v_mfma_f32_16x16x32_bf16 v[12:15], v[166:169], v[178:181], v[12:15]
	v_mfma_f32_16x16x32_bf16 v[8:11], v[156:159], v[178:181], v[8:11]
	v_mfma_f32_16x16x32_bf16 v[4:7], v[110:113], v[178:181], v[4:7]
	v_mfma_f32_16x16x32_bf16 v[0:3], v[106:109], v[178:181], v[0:3]
	s_setprio 0
	v_add_u32_e32 v124, v121, v117
	ds_read_b128 v[106:109], v124 offset:36864
	ds_read_b128 v[110:113], v124 offset:38912
	ds_read_b128 v[156:159], v124 offset:40960
	ds_read_b128 v[166:169], v124 offset:43008
	v_add_u32_e32 v125, v121, v118
	ds_read_b128 v[178:181], v124 offset:45056
	ds_read_b128 v[182:185], v125 offset:57344
	ds_read_b128 v[186:189], v125 offset:59392
	ds_read_b128 v[190:193], v125 offset:61440
	ds_read_b128 v[194:197], v125 offset:63488
	s_setprio 1
	s_waitcnt lgkmcnt(1)
	v_mfma_f32_16x16x32_bf16 v[68:71], v[190:193], v[106:109], v[68:71]
	s_waitcnt lgkmcnt(0)
	v_mfma_f32_16x16x32_bf16 v[64:67], v[194:197], v[106:109], v[64:67]
	v_mfma_f32_16x16x32_bf16 v[60:63], v[182:185], v[110:113], v[60:63]
	v_mfma_f32_16x16x32_bf16 v[56:59], v[186:189], v[110:113], v[56:59]
	v_mfma_f32_16x16x32_bf16 v[52:55], v[190:193], v[110:113], v[52:55]
	v_mfma_f32_16x16x32_bf16 v[48:51], v[194:197], v[110:113], v[48:51]
	v_mfma_f32_16x16x32_bf16 v[44:47], v[182:185], v[156:159], v[44:47]
	v_mfma_f32_16x16x32_bf16 v[40:43], v[186:189], v[156:159], v[40:43]
	v_mfma_f32_16x16x32_bf16 v[36:39], v[190:193], v[156:159], v[36:39]
	v_mfma_f32_16x16x32_bf16 v[32:35], v[194:197], v[156:159], v[32:35]
	v_mfma_f32_16x16x32_bf16 v[28:31], v[182:185], v[166:169], v[28:31]
	v_mfma_f32_16x16x32_bf16 v[24:27], v[186:189], v[166:169], v[24:27]
	v_mfma_f32_16x16x32_bf16 v[20:23], v[190:193], v[166:169], v[20:23]
	v_mfma_f32_16x16x32_bf16 v[16:19], v[194:197], v[166:169], v[16:19]
	v_mfma_f32_16x16x32_bf16 v[12:15], v[182:185], v[178:181], v[12:15]
	v_mfma_f32_16x16x32_bf16 v[8:11], v[186:189], v[178:181], v[8:11]
	v_mfma_f32_16x16x32_bf16 v[4:7], v[190:193], v[178:181], v[4:7]
	v_mfma_f32_16x16x32_bf16 v[0:3], v[194:197], v[178:181], v[0:3]
	v_mfma_f32_16x16x32_bf16 v[198:201], v[182:185], v[106:109], v[76:79]
	v_mfma_f32_16x16x32_bf16 v[206:209], v[186:189], v[106:109], v[72:75]
	s_setprio 0
	s_nop 1
	v_mov_b32_e32 v72, v97
	s_waitcnt vmcnt(0)
	s_barrier
	s_mul_i32 s12, s36, 0xa0
	s_movk_i32 s11, 0x50
	s_mov_b32 s35, 0
	s_lshl_b32 s13, s10, 7
	s_movk_i32 s36, 0x3200
	s_mov_b64 s[38:39], 0x1800
	s_mov_b64 s[10:11], 0x800
	v_ashrrev_i32_e32 v220, 7, v176
	v_mov_b32_e32 v221, 0x50
	v_and_or_b32 v224, v176, 15, s12
	v_mad_u32_u24 v224, v220, v221, v224
	v_and_b32_e32 v220, 64, v176
	v_lshrrev_b32_e32 v221, 2, v176
	v_and_b32_e32 v221, 12, v221
	v_or3_b32 v225, v220, v221, s13
	v_mul_u32_u24_e32 v214, 0x3200, v224
	v_lshl_add_u32 v214, v225, 1, v214
	v_add_u32_e32 v214, 0x1800, v214
	v_lshlrev_b32_e32 v215, 12, v224
	v_lshl_add_u32 v215, v225, 2, v215
	v_mov_b32_e32 v223, 0
	v_mov_b32_e32 v222, v214
	v_lshl_add_u64 v[224:225], v[222:223], 0, s[0:1]
	global_load_dwordx2 v[72:73], v[224:225], off
	global_load_dwordx2 v[74:75], v[224:225], off offset:32
	global_load_dwordx2 v[76:77], v[224:225], off offset:64
	global_load_dwordx2 v[78:79], v[224:225], off offset:96
	v_add_u32_e32 v222, 0x32000, v214
	v_lshl_add_u64 v[224:225], v[222:223], 0, s[0:1]
	global_load_dwordx2 v[106:107], v[224:225], off
	global_load_dwordx2 v[108:109], v[224:225], off offset:32
	global_load_dwordx2 v[110:111], v[224:225], off offset:64
	global_load_dwordx2 v[112:113], v[224:225], off offset:96
	v_add_u32_e32 v222, 0x64000, v214
	v_lshl_add_u64 v[224:225], v[222:223], 0, s[0:1]
	global_load_dwordx2 v[114:115], v[224:225], off
	global_load_dwordx2 v[226:227], v[224:225], off offset:32
	global_load_dwordx2 v[246:247], v[224:225], off offset:64
	global_load_dwordx2 v[248:249], v[224:225], off offset:96
	v_add_u32_e32 v222, 0x96000, v214
	v_lshl_add_u64 v[224:225], v[222:223], 0, s[0:1]
	global_load_dwordx2 v[242:243], v[224:225], off
	global_load_dwordx2 v[244:245], v[224:225], off offset:32
	global_load_dwordx2 v[238:239], v[224:225], off offset:64
	global_load_dwordx2 v[240:241], v[224:225], off offset:96
	v_add_u32_e32 v222, 0xc8000, v214
	v_lshl_add_u64 v[224:225], v[222:223], 0, s[0:1]
	global_load_dwordx2 v[234:235], v[224:225], off
	global_load_dwordx2 v[236:237], v[224:225], off offset:32
	global_load_dwordx2 v[230:231], v[224:225], off offset:64
	global_load_dwordx2 v[232:233], v[224:225], off offset:96
	v_mov_b32_e32 v222, v215
	v_lshl_add_u64 v[218:219], v[222:223], 0, s[4:5]
	s_waitcnt vmcnt(19)
	v_lshlrev_b32_e32 v220, 16, v72
	v_and_b32_e32 v221, 0xffff0000, v72
	v_pk_mul_f32 v[198:199], v[198:199], v[220:221]
	v_lshlrev_b32_e32 v72, 16, v73
	v_and_b32_e32 v73, 0xffff0000, v73
	v_pk_mul_f32 v[200:201], v[200:201], v[72:73]
	s_nop 0
	global_store_dwordx4 v[218:219], v[198:201], off
	s_waitcnt vmcnt(19)
	v_lshlrev_b32_e32 v220, 16, v74
	v_and_b32_e32 v221, 0xffff0000, v74
	v_pk_mul_f32 v[206:207], v[206:207], v[220:221]
	v_lshlrev_b32_e32 v74, 16, v75
	v_and_b32_e32 v75, 0xffff0000, v75
	v_pk_mul_f32 v[208:209], v[208:209], v[74:75]
	s_nop 0
	global_store_dwordx4 v[218:219], v[206:209], off offset:64
	s_waitcnt vmcnt(19)
	v_lshlrev_b32_e32 v220, 16, v76
	v_and_b32_e32 v221, 0xffff0000, v76
	v_pk_mul_f32 v[68:69], v[68:69], v[220:221]
	v_lshlrev_b32_e32 v76, 16, v77
	v_and_b32_e32 v77, 0xffff0000, v77
	v_pk_mul_f32 v[70:71], v[70:71], v[76:77]
	s_nop 0
	global_store_dwordx4 v[218:219], v[68:71], off offset:128
	s_waitcnt vmcnt(19)
	v_lshlrev_b32_e32 v220, 16, v78
	v_and_b32_e32 v221, 0xffff0000, v78
	v_pk_mul_f32 v[64:65], v[64:65], v[220:221]
	v_lshlrev_b32_e32 v78, 16, v79
	v_and_b32_e32 v79, 0xffff0000, v79
	v_pk_mul_f32 v[66:67], v[66:67], v[78:79]
	s_nop 0
	global_store_dwordx4 v[218:219], v[64:67], off offset:192
	v_add_u32_e32 v222, 0x10000, v215
	v_lshl_add_u64 v[218:219], v[222:223], 0, s[4:5]
	s_waitcnt vmcnt(19)
	v_lshlrev_b32_e32 v220, 16, v106
	v_and_b32_e32 v221, 0xffff0000, v106
	v_pk_mul_f32 v[60:61], v[60:61], v[220:221]
	v_lshlrev_b32_e32 v106, 16, v107
	v_and_b32_e32 v107, 0xffff0000, v107
	v_pk_mul_f32 v[62:63], v[62:63], v[106:107]
	s_nop 0
	global_store_dwordx4 v[218:219], v[60:63], off
	s_waitcnt vmcnt(19)
	v_lshlrev_b32_e32 v220, 16, v108
	v_and_b32_e32 v221, 0xffff0000, v108
	v_pk_mul_f32 v[56:57], v[56:57], v[220:221]
	v_lshlrev_b32_e32 v108, 16, v109
	v_and_b32_e32 v109, 0xffff0000, v109
	v_pk_mul_f32 v[58:59], v[58:59], v[108:109]
	s_nop 0
	global_store_dwordx4 v[218:219], v[56:59], off offset:64
	s_waitcnt vmcnt(19)
	v_lshlrev_b32_e32 v220, 16, v110
	v_and_b32_e32 v221, 0xffff0000, v110
	v_pk_mul_f32 v[52:53], v[52:53], v[220:221]
	v_lshlrev_b32_e32 v110, 16, v111
	v_and_b32_e32 v111, 0xffff0000, v111
	v_pk_mul_f32 v[54:55], v[54:55], v[110:111]
	s_nop 0
	global_store_dwordx4 v[218:219], v[52:55], off offset:128
	s_waitcnt vmcnt(19)
	v_lshlrev_b32_e32 v220, 16, v112
	v_and_b32_e32 v221, 0xffff0000, v112
	v_pk_mul_f32 v[48:49], v[48:49], v[220:221]
	v_lshlrev_b32_e32 v112, 16, v113
	v_and_b32_e32 v113, 0xffff0000, v113
	v_pk_mul_f32 v[50:51], v[50:51], v[112:113]
	s_nop 0
	global_store_dwordx4 v[218:219], v[48:51], off offset:192
	v_add_u32_e32 v222, 0x20000, v215
	v_lshl_add_u64 v[218:219], v[222:223], 0, s[4:5]
	s_waitcnt vmcnt(19)
	v_lshlrev_b32_e32 v220, 16, v114
	v_and_b32_e32 v221, 0xffff0000, v114
	v_pk_mul_f32 v[44:45], v[44:45], v[220:221]
	v_lshlrev_b32_e32 v114, 16, v115
	v_and_b32_e32 v115, 0xffff0000, v115
	v_pk_mul_f32 v[46:47], v[46:47], v[114:115]
	s_nop 0
	global_store_dwordx4 v[218:219], v[44:47], off
	s_waitcnt vmcnt(19)
	v_lshlrev_b32_e32 v220, 16, v226
	v_and_b32_e32 v221, 0xffff0000, v226
	v_pk_mul_f32 v[40:41], v[40:41], v[220:221]
	v_lshlrev_b32_e32 v226, 16, v227
	v_and_b32_e32 v227, 0xffff0000, v227
	v_pk_mul_f32 v[42:43], v[42:43], v[226:227]
	s_nop 0
	global_store_dwordx4 v[218:219], v[40:43], off offset:64
	s_waitcnt vmcnt(19)
	v_lshlrev_b32_e32 v220, 16, v246
	v_and_b32_e32 v221, 0xffff0000, v246
	v_pk_mul_f32 v[36:37], v[36:37], v[220:221]
	v_lshlrev_b32_e32 v246, 16, v247
	v_and_b32_e32 v247, 0xffff0000, v247
	v_pk_mul_f32 v[38:39], v[38:39], v[246:247]
	s_nop 0
	global_store_dwordx4 v[218:219], v[36:39], off offset:128
	s_waitcnt vmcnt(19)
	v_lshlrev_b32_e32 v220, 16, v248
	v_and_b32_e32 v221, 0xffff0000, v248
	v_pk_mul_f32 v[32:33], v[32:33], v[220:221]
	v_lshlrev_b32_e32 v248, 16, v249
	v_and_b32_e32 v249, 0xffff0000, v249
	v_pk_mul_f32 v[34:35], v[34:35], v[248:249]
	s_nop 0
	global_store_dwordx4 v[218:219], v[32:35], off offset:192
	v_add_u32_e32 v222, 0x30000, v215
	v_lshl_add_u64 v[218:219], v[222:223], 0, s[4:5]
	s_waitcnt vmcnt(19)
	v_lshlrev_b32_e32 v220, 16, v242
	v_and_b32_e32 v221, 0xffff0000, v242
	v_pk_mul_f32 v[28:29], v[28:29], v[220:221]
	v_lshlrev_b32_e32 v242, 16, v243
	v_and_b32_e32 v243, 0xffff0000, v243
	v_pk_mul_f32 v[30:31], v[30:31], v[242:243]
	s_nop 0
	global_store_dwordx4 v[218:219], v[28:31], off
	s_waitcnt vmcnt(19)
	v_lshlrev_b32_e32 v220, 16, v244
	v_and_b32_e32 v221, 0xffff0000, v244
	v_pk_mul_f32 v[24:25], v[24:25], v[220:221]
	v_lshlrev_b32_e32 v244, 16, v245
	v_and_b32_e32 v245, 0xffff0000, v245
	v_pk_mul_f32 v[26:27], v[26:27], v[244:245]
	s_nop 0
	global_store_dwordx4 v[218:219], v[24:27], off offset:64
	s_waitcnt vmcnt(19)
	v_lshlrev_b32_e32 v220, 16, v238
	v_and_b32_e32 v221, 0xffff0000, v238
	v_pk_mul_f32 v[20:21], v[20:21], v[220:221]
	v_lshlrev_b32_e32 v238, 16, v239
	v_and_b32_e32 v239, 0xffff0000, v239
	v_pk_mul_f32 v[22:23], v[22:23], v[238:239]
	s_nop 0
	global_store_dwordx4 v[218:219], v[20:23], off offset:128
	s_waitcnt vmcnt(19)
	v_lshlrev_b32_e32 v220, 16, v240
	v_and_b32_e32 v221, 0xffff0000, v240
	v_pk_mul_f32 v[16:17], v[16:17], v[220:221]
	v_lshlrev_b32_e32 v240, 16, v241
	v_and_b32_e32 v241, 0xffff0000, v241
	v_pk_mul_f32 v[18:19], v[18:19], v[240:241]
	s_nop 0
	global_store_dwordx4 v[218:219], v[16:19], off offset:192
	v_add_u32_e32 v222, 0x40000, v215
	v_lshl_add_u64 v[218:219], v[222:223], 0, s[4:5]
	s_waitcnt vmcnt(19)
	v_lshlrev_b32_e32 v220, 16, v234
	v_and_b32_e32 v221, 0xffff0000, v234
	v_pk_mul_f32 v[12:13], v[12:13], v[220:221]
	v_lshlrev_b32_e32 v234, 16, v235
	v_and_b32_e32 v235, 0xffff0000, v235
	v_pk_mul_f32 v[14:15], v[14:15], v[234:235]
	s_nop 0
	global_store_dwordx4 v[218:219], v[12:15], off
	s_waitcnt vmcnt(19)
	v_lshlrev_b32_e32 v220, 16, v236
	v_and_b32_e32 v221, 0xffff0000, v236
	v_pk_mul_f32 v[8:9], v[8:9], v[220:221]
	v_lshlrev_b32_e32 v236, 16, v237
	v_and_b32_e32 v237, 0xffff0000, v237
	v_pk_mul_f32 v[10:11], v[10:11], v[236:237]
	s_nop 0
	global_store_dwordx4 v[218:219], v[8:11], off offset:64
	s_waitcnt vmcnt(19)
	v_lshlrev_b32_e32 v220, 16, v230
	v_and_b32_e32 v221, 0xffff0000, v230
	v_pk_mul_f32 v[4:5], v[4:5], v[220:221]
	v_lshlrev_b32_e32 v230, 16, v231
	v_and_b32_e32 v231, 0xffff0000, v231
	v_pk_mul_f32 v[6:7], v[6:7], v[230:231]
	s_nop 0
	global_store_dwordx4 v[218:219], v[4:7], off offset:128
	s_waitcnt vmcnt(19)
	v_lshlrev_b32_e32 v220, 16, v232
	v_and_b32_e32 v221, 0xffff0000, v232
	v_pk_mul_f32 v[0:1], v[0:1], v[220:221]
	v_lshlrev_b32_e32 v232, 16, v233
	v_and_b32_e32 v233, 0xffff0000, v233
	v_pk_mul_f32 v[2:3], v[2:3], v[232:233]
	s_nop 0
	global_store_dwordx4 v[218:219], v[0:3], off offset:192
	s_nop 1
	v_lshl_add_u64 v[0:1], v[104:105], 0, s[10:11]
	v_readfirstlane_b32 s10, v81
	s_mov_b32 m0, s10
	s_mov_b64 s[10:11], 0x64800
	global_load_lds_dwordx4 v[0:1], off
	v_lshl_add_u64 v[0:1], v[104:105], 0, s[10:11]
	v_readfirstlane_b32 s10, v133
	s_mov_b32 m0, s10
	s_mov_b64 s[10:11], 0xc8800
	global_load_lds_dwordx4 v[0:1], off
	v_lshl_add_u64 v[0:1], v[104:105], 0, s[10:11]
	v_readfirstlane_b32 s10, v132
	s_mov_b32 m0, s10
	s_mov_b64 s[10:11], 0x12c800
	global_load_lds_dwordx4 v[0:1], off
	v_lshl_add_u64 v[0:1], v[104:105], 0, s[10:11]
	v_readfirstlane_b32 s10, v131
	s_mov_b32 m0, s10
	s_mov_b64 s[10:11], 0x190800
	global_load_lds_dwordx4 v[0:1], off
	v_lshl_add_u64 v[0:1], v[104:105], 0, s[10:11]
	v_readfirstlane_b32 s10, v130
	s_mov_b32 m0, s10
	v_readfirstlane_b32 s10, v129
	global_load_lds_dwordx4 v[0:1], off
	v_lshl_add_u64 v[0:1], v[86:87], 0, s[8:9]
	s_mov_b32 m0, s10
	v_readfirstlane_b32 s10, v128
	global_load_lds_dwordx4 v[0:1], off
	v_lshl_add_u64 v[2:3], v[0:1], 0, s[40:41]
	s_mov_b32 m0, s10
	s_mov_b64 s[10:11], 0x20000
	global_load_lds_dwordx4 v[2:3], off
	v_lshl_add_u64 v[2:3], v[0:1], 0, s[10:11]
	v_readfirstlane_b32 s10, v127
	s_mov_b32 m0, s10
	s_mov_b64 s[10:11], 0x30000
	v_lshl_add_u64 v[0:1], v[0:1], 0, s[10:11]
	v_readfirstlane_b32 s10, v126
	global_load_lds_dwordx4 v[2:3], off
	s_mov_b32 m0, s10
	s_mov_b64 s[10:11], 0
	global_load_lds_dwordx4 v[0:1], off
	s_nop 0
	v_mov_b32_e32 v0, 0
	v_mov_b32_e32 v1, v0
	v_mov_b32_e32 v2, v0
	v_mov_b32_e32 v3, v0
	v_mov_b32_e32 v4, v0
	v_mov_b32_e32 v5, v0
	v_mov_b32_e32 v6, v0
	v_mov_b32_e32 v7, v0
	v_mov_b32_e32 v8, v0
	v_mov_b32_e32 v9, v0
	v_mov_b32_e32 v10, v0
	v_mov_b32_e32 v11, v0
	v_mov_b32_e32 v12, v0
	v_mov_b32_e32 v13, v0
	v_mov_b32_e32 v14, v0
	v_mov_b32_e32 v15, v0
	v_mov_b32_e32 v16, v0
	v_mov_b32_e32 v17, v0
	v_mov_b32_e32 v18, v0
	v_mov_b32_e32 v19, v0
	v_mov_b32_e32 v20, v0
	v_mov_b32_e32 v21, v0
	v_mov_b32_e32 v22, v0
	v_mov_b32_e32 v23, v0
	v_mov_b32_e32 v24, v0
	v_mov_b32_e32 v25, v0
	v_mov_b32_e32 v26, v0
	v_mov_b32_e32 v27, v0
	v_mov_b32_e32 v28, v0
	v_mov_b32_e32 v29, v0
	v_mov_b32_e32 v30, v0
	v_mov_b32_e32 v31, v0
	v_mov_b32_e32 v32, v0
	v_mov_b32_e32 v33, v0
	v_mov_b32_e32 v34, v0
	v_mov_b32_e32 v35, v0
	v_mov_b32_e32 v36, v0
	v_mov_b32_e32 v37, v0
	v_mov_b32_e32 v38, v0
	v_mov_b32_e32 v39, v0
	v_mov_b32_e32 v40, v0
	v_mov_b32_e32 v41, v0
	v_mov_b32_e32 v42, v0
	v_mov_b32_e32 v43, v0
	v_mov_b32_e32 v44, v0
	v_mov_b32_e32 v45, v0
	v_mov_b32_e32 v46, v0
	v_mov_b32_e32 v47, v0
	v_mov_b32_e32 v48, v0
	v_mov_b32_e32 v49, v0
	v_mov_b32_e32 v50, v0
	v_mov_b32_e32 v51, v0
	v_mov_b32_e32 v52, v0
	v_mov_b32_e32 v53, v0
	v_mov_b32_e32 v54, v0
	v_mov_b32_e32 v55, v0
	v_mov_b32_e32 v56, v0
	v_mov_b32_e32 v57, v0
	v_mov_b32_e32 v58, v0
	v_mov_b32_e32 v59, v0
	v_mov_b32_e32 v60, v0
	v_mov_b32_e32 v61, v0
	v_mov_b32_e32 v62, v0
	v_mov_b32_e32 v63, v0
	v_mov_b32_e32 v64, v0
	v_mov_b32_e32 v65, v0
	v_mov_b32_e32 v66, v0
	v_mov_b32_e32 v67, v0
	v_mov_b32_e32 v68, v0
	v_mov_b32_e32 v69, v0
	v_mov_b32_e32 v70, v0
	v_mov_b32_e32 v71, v0
	v_mov_b32_e32 v72, v0
	v_mov_b32_e32 v73, v0
	v_mov_b32_e32 v74, v0
	v_mov_b32_e32 v75, v0
	v_mov_b32_e32 v76, v0
	v_mov_b32_e32 v77, v0
	v_mov_b32_e32 v78, v0
	v_mov_b32_e32 v79, v0
	s_nop 0
	s_nop 0
	s_mov_b32 s37, 0x9000
	v_add_u32_e32 v204, s37, v81
	v_lshl_add_u64 v[202:203], v[94:95], 0, s[10:11]
	s_mov_b64 s[38:39], 0x6181880
	v_readfirstlane_b32 s37, v204
	v_add_u32_e32 v228, 0x1000, v204
	v_lshl_add_u64 v[210:211], v[202:203], 0, s[38:39]
	s_mov_b32 m0, s37
	s_mov_b64 s[38:39], 0x61e5880
	v_readfirstlane_b32 s37, v228
	v_add_u32_e32 v228, 0x2000, v204
	global_load_lds_dwordx4 v[210:211], off
	v_lshl_add_u64 v[210:211], v[202:203], 0, s[38:39]
	s_mov_b32 m0, s37
	s_mov_b64 s[38:39], 0x6249880
	v_readfirstlane_b32 s37, v228
	v_add_u32_e32 v228, 0x3000, v204
	global_load_lds_dwordx4 v[210:211], off
	v_lshl_add_u64 v[210:211], v[202:203], 0, s[38:39]
	s_mov_b32 m0, s37
	s_mov_b64 s[38:39], 0x62ad880
	v_readfirstlane_b32 s37, v228
	global_load_lds_dwordx4 v[210:211], off
	v_lshl_add_u64 v[210:211], v[202:203], 0, s[38:39]
	s_mov_b32 m0, s37
	s_mov_b64 s[38:39], 0x6311880
	global_load_lds_dwordx4 v[210:211], off
	v_add_u32_e32 v210, 0x4000, v204
	v_lshl_add_u64 v[202:203], v[202:203], 0, s[38:39]
	v_readfirstlane_b32 s37, v210
	s_mov_b32 m0, s37
	v_add_u32_e32 v228, 0x5000, v204
	global_load_lds_dwordx4 v[202:203], off
	v_lshl_add_u64 v[202:203], v[100:101], 0, s[10:11]
	s_mov_b64 s[38:39], 0x14731080
	v_readfirstlane_b32 s37, v228
	v_add_u32_e32 v228, 0x6000, v204
	v_lshl_add_u64 v[210:211], v[202:203], 0, s[38:39]
	s_mov_b32 m0, s37
	s_mov_b64 s[38:39], 0x14741080
	v_readfirstlane_b32 s37, v228
	v_add_u32_e32 v228, 0x7000, v204
	global_load_lds_dwordx4 v[210:211], off
	v_lshl_add_u64 v[210:211], v[202:203], 0, s[38:39]
	s_mov_b32 m0, s37
	s_mov_b64 s[38:39], 0x14751080
	v_readfirstlane_b32 s37, v228
	global_load_lds_dwordx4 v[210:211], off
	v_lshl_add_u64 v[210:211], v[202:203], 0, s[38:39]
	s_mov_b32 m0, s37
	s_mov_b64 s[38:39], 0x14761080
	global_load_lds_dwordx4 v[210:211], off
	v_add_u32_e32 v210, 0x8000, v204
	v_lshl_add_u64 v[202:203], v[202:203], 0, s[38:39]
	v_readfirstlane_b32 s37, v210
	s_mov_b32 m0, s37
	s_nop 0
	global_load_lds_dwordx4 v[202:203], off
	s_waitcnt vmcnt(9) lgkmcnt(0)
	s_barrier
.LBB0_88:
	s_add_i32 s36, s35, 1
	s_bitcmp1_b32 s35, 0
	s_cselect_b32 s35, 0x9000, 0
	s_add_i32 s35, s35, 0
	v_add_u32_e32 v166, s35, v116
	v_add_u32_e32 v167, v166, v117
	ds_read_b128 v[104:107], v167
	ds_read_b128 v[108:111], v167 offset:2048
	ds_read_b128 v[112:115], v167 offset:4096
	ds_read_b128 v[156:159], v167 offset:6144
	v_add_u32_e32 v177, v166, v118
	ds_read_b128 v[166:169], v167 offset:8192
	ds_read_b128 v[178:181], v177 offset:20480
	ds_read_b128 v[182:185], v177 offset:22528
	ds_read_b128 v[186:189], v177 offset:24576
	ds_read_b128 v[190:193], v177 offset:26624
	v_add_u32_e32 v210, s35, v119
	v_add_u32_e32 v211, v210, v117
	ds_read_b128 v[212:215], v211
	ds_read_b128 v[216:219], v211 offset:2048
	ds_read_b128 v[220:223], v211 offset:4096
	ds_read_b128 v[224:227], v211 offset:6144
	v_add_u32_e32 v228, v210, v118
	ds_read_b128 v[230:233], v211 offset:8192
	ds_read_b128 v[234:237], v228 offset:20480
	ds_read_b128 v[238:241], v228 offset:22528
	ds_read_b128 v[242:245], v228 offset:24576
	ds_read_b128 v[246:249], v228 offset:26624
	s_setprio 1
	s_waitcnt lgkmcnt(9)
	v_mfma_f32_16x16x32_bf16 v[76:79], v[178:181], v[104:107], v[76:79]
	v_mfma_f32_16x16x32_bf16 v[72:75], v[182:185], v[104:107], v[72:75]
	v_mfma_f32_16x16x32_bf16 v[68:71], v[186:189], v[104:107], v[68:71]
	v_mfma_f32_16x16x32_bf16 v[64:67], v[190:193], v[104:107], v[64:67]
	v_mfma_f32_16x16x32_bf16 v[60:63], v[178:181], v[108:111], v[60:63]
	v_mfma_f32_16x16x32_bf16 v[56:59], v[182:185], v[108:111], v[56:59]
	v_mfma_f32_16x16x32_bf16 v[52:55], v[186:189], v[108:111], v[52:55]
	v_mfma_f32_16x16x32_bf16 v[48:51], v[190:193], v[108:111], v[48:51]
	v_mfma_f32_16x16x32_bf16 v[44:47], v[178:181], v[112:115], v[44:47]
	v_mfma_f32_16x16x32_bf16 v[40:43], v[182:185], v[112:115], v[40:43]
	v_mfma_f32_16x16x32_bf16 v[36:39], v[186:189], v[112:115], v[36:39]
	v_mfma_f32_16x16x32_bf16 v[32:35], v[190:193], v[112:115], v[32:35]
	v_mfma_f32_16x16x32_bf16 v[28:31], v[178:181], v[156:159], v[28:31]
	v_mfma_f32_16x16x32_bf16 v[24:27], v[182:185], v[156:159], v[24:27]
	v_mfma_f32_16x16x32_bf16 v[20:23], v[186:189], v[156:159], v[20:23]
	v_mfma_f32_16x16x32_bf16 v[16:19], v[190:193], v[156:159], v[16:19]
	v_mfma_f32_16x16x32_bf16 v[12:15], v[178:181], v[166:169], v[12:15]
	v_mfma_f32_16x16x32_bf16 v[8:11], v[182:185], v[166:169], v[8:11]
	v_mfma_f32_16x16x32_bf16 v[4:7], v[186:189], v[166:169], v[4:7]
	v_mfma_f32_16x16x32_bf16 v[0:3], v[190:193], v[166:169], v[0:3]
	s_setprio 0
	s_setprio 1
	s_waitcnt lgkmcnt(0)
	s_setprio 0
	s_barrier
	s_add_u32 s10, s10, 0x80
	s_addc_u32 s11, s11, 0
	s_mov_b32 s37, s35
	v_add_u32_e32 v204, s37, v81
	v_lshl_add_u64 v[202:203], v[94:95], 0, s[10:11]
	s_mov_b64 s[38:39], 0x6181880
	v_readfirstlane_b32 s37, v204
	v_add_u32_e32 v228, 0x1000, v204
	v_lshl_add_u64 v[210:211], v[202:203], 0, s[38:39]
	s_mov_b32 m0, s37
	s_mov_b64 s[38:39], 0x61e5880
	v_readfirstlane_b32 s37, v228
	v_add_u32_e32 v228, 0x2000, v204
	global_load_lds_dwordx4 v[210:211], off
	v_lshl_add_u64 v[210:211], v[202:203], 0, s[38:39]
	s_mov_b32 m0, s37
	s_mov_b64 s[38:39], 0x6249880
	v_readfirstlane_b32 s37, v228
	v_add_u32_e32 v228, 0x3000, v204
	global_load_lds_dwordx4 v[210:211], off
	v_lshl_add_u64 v[210:211], v[202:203], 0, s[38:39]
	s_mov_b32 m0, s37
	s_mov_b64 s[38:39], 0x62ad880
	v_readfirstlane_b32 s37, v228
	global_load_lds_dwordx4 v[210:211], off
	v_lshl_add_u64 v[210:211], v[202:203], 0, s[38:39]
	s_mov_b32 m0, s37
	s_mov_b64 s[38:39], 0x6311880
	global_load_lds_dwordx4 v[210:211], off
	v_add_u32_e32 v210, 0x4000, v204
	v_lshl_add_u64 v[202:203], v[202:203], 0, s[38:39]
	v_readfirstlane_b32 s37, v210
	s_mov_b32 m0, s37
	v_add_u32_e32 v228, 0x5000, v204
	global_load_lds_dwordx4 v[202:203], off
	v_lshl_add_u64 v[202:203], v[100:101], 0, s[10:11]
	s_mov_b64 s[38:39], 0x14731080
	v_readfirstlane_b32 s37, v228
	v_add_u32_e32 v228, 0x6000, v204
	v_lshl_add_u64 v[210:211], v[202:203], 0, s[38:39]
	s_mov_b32 m0, s37
	s_mov_b64 s[38:39], 0x14741080
	v_readfirstlane_b32 s37, v228
	v_add_u32_e32 v228, 0x7000, v204
	global_load_lds_dwordx4 v[210:211], off
	v_lshl_add_u64 v[210:211], v[202:203], 0, s[38:39]
	s_mov_b32 m0, s37
	s_mov_b64 s[38:39], 0x14751080
	v_readfirstlane_b32 s37, v228
	global_load_lds_dwordx4 v[210:211], off
	v_lshl_add_u64 v[210:211], v[202:203], 0, s[38:39]
	s_mov_b32 m0, s37
	s_mov_b64 s[38:39], 0x14761080
	global_load_lds_dwordx4 v[210:211], off
	v_add_u32_e32 v210, 0x8000, v204
	v_lshl_add_u64 v[202:203], v[202:203], 0, s[38:39]
	v_readfirstlane_b32 s37, v210
	s_mov_b32 m0, s37
	s_nop 0
	global_load_lds_dwordx4 v[202:203], off
	s_setprio 1
	v_mfma_f32_16x16x32_bf16 v[76:79], v[234:237], v[212:215], v[76:79]
	v_mfma_f32_16x16x32_bf16 v[72:75], v[238:241], v[212:215], v[72:75]
	v_mfma_f32_16x16x32_bf16 v[68:71], v[242:245], v[212:215], v[68:71]
	v_mfma_f32_16x16x32_bf16 v[64:67], v[246:249], v[212:215], v[64:67]
	v_mfma_f32_16x16x32_bf16 v[60:63], v[234:237], v[216:219], v[60:63]
	v_mfma_f32_16x16x32_bf16 v[56:59], v[238:241], v[216:219], v[56:59]
	v_mfma_f32_16x16x32_bf16 v[52:55], v[242:245], v[216:219], v[52:55]
	v_mfma_f32_16x16x32_bf16 v[48:51], v[246:249], v[216:219], v[48:51]
	v_mfma_f32_16x16x32_bf16 v[44:47], v[234:237], v[220:223], v[44:47]
	v_mfma_f32_16x16x32_bf16 v[40:43], v[238:241], v[220:223], v[40:43]
	v_mfma_f32_16x16x32_bf16 v[36:39], v[242:245], v[220:223], v[36:39]
	v_mfma_f32_16x16x32_bf16 v[32:35], v[246:249], v[220:223], v[32:35]
	v_mfma_f32_16x16x32_bf16 v[28:31], v[234:237], v[224:227], v[28:31]
	v_mfma_f32_16x16x32_bf16 v[24:27], v[238:241], v[224:227], v[24:27]
	v_mfma_f32_16x16x32_bf16 v[20:23], v[242:245], v[224:227], v[20:23]
	v_mfma_f32_16x16x32_bf16 v[16:19], v[246:249], v[224:227], v[16:19]
	v_mfma_f32_16x16x32_bf16 v[12:15], v[234:237], v[230:233], v[12:15]
	v_mfma_f32_16x16x32_bf16 v[8:11], v[238:241], v[230:233], v[8:11]
	v_mfma_f32_16x16x32_bf16 v[4:7], v[242:245], v[230:233], v[4:7]
	v_mfma_f32_16x16x32_bf16 v[0:3], v[246:249], v[230:233], v[0:3]
	s_setprio 0
	s_cmpk_lg_i32 s10, 0x700
	s_mov_b32 s35, s36
	s_waitcnt vmcnt(9)
	s_barrier
	s_cbranch_scc1 .LBB0_88
	s_add_i32 s36, s35, 1
	s_bitcmp1_b32 s35, 0
	s_cselect_b32 s35, 0x9000, 0
	s_add_i32 s35, s35, 0
	v_add_u32_e32 v166, s35, v116
	v_add_u32_e32 v167, v166, v117
	ds_read_b128 v[104:107], v167
	ds_read_b128 v[108:111], v167 offset:2048
	ds_read_b128 v[112:115], v167 offset:4096
	ds_read_b128 v[156:159], v167 offset:6144
	v_add_u32_e32 v177, v166, v118
	ds_read_b128 v[166:169], v167 offset:8192
	ds_read_b128 v[178:181], v177 offset:20480
	ds_read_b128 v[182:185], v177 offset:22528
	ds_read_b128 v[186:189], v177 offset:24576
	ds_read_b128 v[190:193], v177 offset:26624
	v_add_u32_e32 v210, s35, v119
	v_add_u32_e32 v211, v210, v117
	ds_read_b128 v[212:215], v211
	ds_read_b128 v[216:219], v211 offset:2048
	ds_read_b128 v[220:223], v211 offset:4096
	ds_read_b128 v[224:227], v211 offset:6144
	v_add_u32_e32 v228, v210, v118
	ds_read_b128 v[230:233], v211 offset:8192
	ds_read_b128 v[234:237], v228 offset:20480
	ds_read_b128 v[238:241], v228 offset:22528
	ds_read_b128 v[242:245], v228 offset:24576
	ds_read_b128 v[246:249], v228 offset:26624
	s_setprio 1
	s_waitcnt lgkmcnt(9)
	v_mfma_f32_16x16x32_bf16 v[76:79], v[178:181], v[104:107], v[76:79]
	v_mfma_f32_16x16x32_bf16 v[72:75], v[182:185], v[104:107], v[72:75]
	v_mfma_f32_16x16x32_bf16 v[68:71], v[186:189], v[104:107], v[68:71]
	v_mfma_f32_16x16x32_bf16 v[64:67], v[190:193], v[104:107], v[64:67]
	v_mfma_f32_16x16x32_bf16 v[60:63], v[178:181], v[108:111], v[60:63]
	v_mfma_f32_16x16x32_bf16 v[56:59], v[182:185], v[108:111], v[56:59]
	v_mfma_f32_16x16x32_bf16 v[52:55], v[186:189], v[108:111], v[52:55]
	v_mfma_f32_16x16x32_bf16 v[48:51], v[190:193], v[108:111], v[48:51]
	v_mfma_f32_16x16x32_bf16 v[44:47], v[178:181], v[112:115], v[44:47]
	v_mfma_f32_16x16x32_bf16 v[40:43], v[182:185], v[112:115], v[40:43]
	v_mfma_f32_16x16x32_bf16 v[36:39], v[186:189], v[112:115], v[36:39]
	v_mfma_f32_16x16x32_bf16 v[32:35], v[190:193], v[112:115], v[32:35]
	v_mfma_f32_16x16x32_bf16 v[28:31], v[178:181], v[156:159], v[28:31]
	v_mfma_f32_16x16x32_bf16 v[24:27], v[182:185], v[156:159], v[24:27]
	v_mfma_f32_16x16x32_bf16 v[20:23], v[186:189], v[156:159], v[20:23]
	v_mfma_f32_16x16x32_bf16 v[16:19], v[190:193], v[156:159], v[16:19]
	v_mfma_f32_16x16x32_bf16 v[12:15], v[178:181], v[166:169], v[12:15]
	v_mfma_f32_16x16x32_bf16 v[8:11], v[182:185], v[166:169], v[8:11]
	v_mfma_f32_16x16x32_bf16 v[4:7], v[186:189], v[166:169], v[4:7]
	v_mfma_f32_16x16x32_bf16 v[0:3], v[190:193], v[166:169], v[0:3]
	s_setprio 0
	s_setprio 1
	s_waitcnt lgkmcnt(0)
	v_mfma_f32_16x16x32_bf16 v[76:79], v[234:237], v[212:215], v[76:79]
	v_mfma_f32_16x16x32_bf16 v[72:75], v[238:241], v[212:215], v[72:75]
	v_mfma_f32_16x16x32_bf16 v[68:71], v[242:245], v[212:215], v[68:71]
	v_mfma_f32_16x16x32_bf16 v[64:67], v[246:249], v[212:215], v[64:67]
	v_mfma_f32_16x16x32_bf16 v[60:63], v[234:237], v[216:219], v[60:63]
	v_mfma_f32_16x16x32_bf16 v[56:59], v[238:241], v[216:219], v[56:59]
	v_mfma_f32_16x16x32_bf16 v[52:55], v[242:245], v[216:219], v[52:55]
	v_mfma_f32_16x16x32_bf16 v[48:51], v[246:249], v[216:219], v[48:51]
	v_mfma_f32_16x16x32_bf16 v[44:47], v[234:237], v[220:223], v[44:47]
	v_mfma_f32_16x16x32_bf16 v[40:43], v[238:241], v[220:223], v[40:43]
	v_mfma_f32_16x16x32_bf16 v[36:39], v[242:245], v[220:223], v[36:39]
	v_mfma_f32_16x16x32_bf16 v[32:35], v[246:249], v[220:223], v[32:35]
	v_mfma_f32_16x16x32_bf16 v[28:31], v[234:237], v[224:227], v[28:31]
	v_mfma_f32_16x16x32_bf16 v[24:27], v[238:241], v[224:227], v[24:27]
	v_mfma_f32_16x16x32_bf16 v[20:23], v[242:245], v[224:227], v[20:23]
	v_mfma_f32_16x16x32_bf16 v[16:19], v[246:249], v[224:227], v[16:19]
	v_mfma_f32_16x16x32_bf16 v[12:15], v[234:237], v[230:233], v[12:15]
	v_mfma_f32_16x16x32_bf16 v[8:11], v[238:241], v[230:233], v[8:11]
	v_mfma_f32_16x16x32_bf16 v[4:7], v[242:245], v[230:233], v[4:7]
	v_mfma_f32_16x16x32_bf16 v[0:3], v[246:249], v[230:233], v[0:3]
	s_setprio 0
	s_add_u32 s10, s10, 0x80
	s_addc_u32 s11, s11, 0
	s_mov_b32 s35, s36
	s_waitcnt vmcnt(0)
	s_barrier
	ds_read_b128 v[104:107], v122 offset:63488
	ds_read_b128 v[108:111], v122 offset:61440
	ds_read_b128 v[112:115], v122 offset:59392
	ds_read_b128 v[156:159], v122 offset:57344
	ds_read_b128 v[166:169], v123 offset:45056
	ds_read_b128 v[178:181], v123 offset:43008
	ds_read_b128 v[182:185], v123 offset:40960
	ds_read_b128 v[186:189], v123 offset:38912
	ds_read_b128 v[190:193], v123 offset:36864
	s_setprio 1
	s_waitcnt lgkmcnt(0)
	v_mfma_f32_16x16x32_bf16 v[76:79], v[156:159], v[190:193], v[76:79]
	v_mfma_f32_16x16x32_bf16 v[72:75], v[112:115], v[190:193], v[72:75]
	v_mfma_f32_16x16x32_bf16 v[68:71], v[108:111], v[190:193], v[68:71]
	v_mfma_f32_16x16x32_bf16 v[64:67], v[104:107], v[190:193], v[64:67]
	v_mfma_f32_16x16x32_bf16 v[60:63], v[156:159], v[186:189], v[60:63]
	v_mfma_f32_16x16x32_bf16 v[56:59], v[112:115], v[186:189], v[56:59]
	v_mfma_f32_16x16x32_bf16 v[52:55], v[108:111], v[186:189], v[52:55]
	v_mfma_f32_16x16x32_bf16 v[48:51], v[104:107], v[186:189], v[48:51]
	v_mfma_f32_16x16x32_bf16 v[44:47], v[156:159], v[182:185], v[44:47]
	v_mfma_f32_16x16x32_bf16 v[40:43], v[112:115], v[182:185], v[40:43]
	v_mfma_f32_16x16x32_bf16 v[36:39], v[108:111], v[182:185], v[36:39]
	v_mfma_f32_16x16x32_bf16 v[32:35], v[104:107], v[182:185], v[32:35]
	v_mfma_f32_16x16x32_bf16 v[28:31], v[156:159], v[178:181], v[28:31]
	v_mfma_f32_16x16x32_bf16 v[24:27], v[112:115], v[178:181], v[24:27]
	v_mfma_f32_16x16x32_bf16 v[20:23], v[108:111], v[178:181], v[20:23]
	v_mfma_f32_16x16x32_bf16 v[16:19], v[104:107], v[178:181], v[16:19]
	v_mfma_f32_16x16x32_bf16 v[12:15], v[156:159], v[166:169], v[12:15]
	v_mfma_f32_16x16x32_bf16 v[8:11], v[112:115], v[166:169], v[8:11]
	v_mfma_f32_16x16x32_bf16 v[4:7], v[108:111], v[166:169], v[4:7]
	v_mfma_f32_16x16x32_bf16 v[0:3], v[104:107], v[166:169], v[0:3]
	s_setprio 0
	ds_read_b128 v[104:107], v124 offset:36864
	ds_read_b128 v[108:111], v124 offset:38912
	ds_read_b128 v[112:115], v124 offset:40960
	ds_read_b128 v[156:159], v124 offset:43008
	ds_read_b128 v[166:169], v124 offset:45056
	ds_read_b128 v[178:181], v125 offset:57344
	ds_read_b128 v[182:185], v125 offset:59392
	ds_read_b128 v[186:189], v125 offset:61440
	ds_read_b128 v[190:193], v125 offset:63488
	s_setprio 1
	s_waitcnt lgkmcnt(3)
	v_mfma_f32_16x16x32_bf16 v[76:79], v[178:181], v[104:107], v[76:79]
	s_waitcnt lgkmcnt(0)
	v_mfma_f32_16x16x32_bf16 v[64:67], v[190:193], v[104:107], v[64:67]
	v_mfma_f32_16x16x32_bf16 v[60:63], v[178:181], v[108:111], v[60:63]
	v_mfma_f32_16x16x32_bf16 v[56:59], v[182:185], v[108:111], v[56:59]
	v_mfma_f32_16x16x32_bf16 v[52:55], v[186:189], v[108:111], v[52:55]
	v_mfma_f32_16x16x32_bf16 v[48:51], v[190:193], v[108:111], v[48:51]
	v_mfma_f32_16x16x32_bf16 v[44:47], v[178:181], v[112:115], v[44:47]
	v_mfma_f32_16x16x32_bf16 v[40:43], v[182:185], v[112:115], v[40:43]
	v_mfma_f32_16x16x32_bf16 v[36:39], v[186:189], v[112:115], v[36:39]
	v_mfma_f32_16x16x32_bf16 v[32:35], v[190:193], v[112:115], v[32:35]
	v_mfma_f32_16x16x32_bf16 v[28:31], v[178:181], v[156:159], v[28:31]
	v_mfma_f32_16x16x32_bf16 v[24:27], v[182:185], v[156:159], v[24:27]
	v_mfma_f32_16x16x32_bf16 v[20:23], v[186:189], v[156:159], v[20:23]
	v_mfma_f32_16x16x32_bf16 v[16:19], v[190:193], v[156:159], v[16:19]
	v_mfma_f32_16x16x32_bf16 v[12:15], v[178:181], v[166:169], v[12:15]
	v_mfma_f32_16x16x32_bf16 v[8:11], v[182:185], v[166:169], v[8:11]
	v_mfma_f32_16x16x32_bf16 v[4:7], v[186:189], v[166:169], v[4:7]
	v_mfma_f32_16x16x32_bf16 v[0:3], v[190:193], v[166:169], v[0:3]
	v_mfma_f32_16x16x32_bf16 v[194:197], v[182:185], v[104:107], v[72:75]
	v_mfma_f32_16x16x32_bf16 v[198:201], v[186:189], v[104:107], v[68:71]
	s_setprio 0
	s_nop 1
	v_mov_b32_e32 v68, v97
	s_waitcnt vmcnt(0)
	s_barrier
	s_movk_i32 s11, 0x50
	s_mov_b32 s10, 0
	s_movk_i32 s11, 0x3200
	s_mov_b64 s[38:39], 0x2000
	s_mov_b64 s[36:37], 0x1000
	v_readfirstlane_b32 s11, v81
	s_mov_b32 m0, s11
	v_readfirstlane_b32 s11, v133
	v_ashrrev_i32_e32 v218, 7, v176
	v_mov_b32_e32 v219, 0x50
	v_and_or_b32 v222, v176, 15, s12
	v_mad_u32_u24 v222, v218, v219, v222
	v_and_b32_e32 v218, 64, v176
	v_lshrrev_b32_e32 v219, 2, v176
	v_and_b32_e32 v219, 12, v219
	v_or3_b32 v223, v218, v219, s13
	v_mul_u32_u24_e32 v204, 0x3200, v222
	v_lshl_add_u32 v204, v223, 1, v204
	v_add_u32_e32 v204, 0x2000, v204
	v_lshlrev_b32_e32 v228, 12, v222
	v_lshl_add_u32 v228, v223, 2, v228
	v_mov_b32_e32 v233, 0
	v_mov_b32_e32 v232, v204
	v_lshl_add_u64 v[222:223], v[232:233], 0, s[0:1]
	global_load_dwordx2 v[68:69], v[222:223], off
	global_load_dwordx2 v[70:71], v[222:223], off offset:32
	global_load_dwordx2 v[72:73], v[222:223], off offset:64
	global_load_dwordx2 v[74:75], v[222:223], off offset:96
	v_add_u32_e32 v232, 0x32000, v204
	v_lshl_add_u64 v[222:223], v[232:233], 0, s[0:1]
	global_load_dwordx2 v[106:107], v[222:223], off
	global_load_dwordx2 v[108:109], v[222:223], off offset:32
	global_load_dwordx2 v[110:111], v[222:223], off offset:64
	global_load_dwordx2 v[112:113], v[222:223], off offset:96
	v_add_u32_e32 v232, 0x64000, v204
	v_lshl_add_u64 v[222:223], v[232:233], 0, s[0:1]
	global_load_dwordx2 v[114:115], v[222:223], off
	global_load_dwordx2 v[202:203], v[222:223], off offset:32
	global_load_dwordx2 v[226:227], v[222:223], off offset:64
	global_load_dwordx2 v[246:247], v[222:223], off offset:96
	v_add_u32_e32 v232, 0x96000, v204
	v_lshl_add_u64 v[222:223], v[232:233], 0, s[0:1]
	global_load_dwordx2 v[248:249], v[222:223], off
	global_load_dwordx2 v[242:243], v[222:223], off offset:32
	global_load_dwordx2 v[244:245], v[222:223], off offset:64
	global_load_dwordx2 v[238:239], v[222:223], off offset:96
	v_add_u32_e32 v232, 0xc8000, v204
	v_lshl_add_u64 v[222:223], v[232:233], 0, s[0:1]
	global_load_dwordx2 v[240:241], v[222:223], off
	global_load_dwordx2 v[234:235], v[222:223], off offset:32
	global_load_dwordx2 v[236:237], v[222:223], off offset:64
	global_load_dwordx2 v[230:231], v[222:223], off offset:96
	v_mov_b32_e32 v232, v228
	v_lshl_add_u64 v[222:223], v[232:233], 0, s[4:5]
	global_load_dwordx4 v[156:159], v[222:223], off
	global_load_dwordx4 v[166:169], v[222:223], off offset:64
	global_load_dwordx4 v[178:181], v[222:223], off offset:128
	global_load_dwordx4 v[182:185], v[222:223], off offset:192
	v_add_u32_e32 v232, 0x10000, v228
	v_lshl_add_u64 v[222:223], v[232:233], 0, s[4:5]
	global_load_dwordx4 v[186:189], v[222:223], off
	global_load_dwordx4 v[190:193], v[222:223], off offset:64
	global_load_dwordx4 v[210:213], v[222:223], off offset:128
	global_load_dwordx4 v[214:217], v[222:223], off offset:192
	v_mov_b32_e32 v232, v228
	v_lshl_add_u64 v[224:225], v[232:233], 0, s[4:5]
	s_waitcnt vmcnt(7)
	v_lshlrev_b32_e32 v218, 16, v68
	v_and_b32_e32 v219, 0xffff0000, v68
	v_pk_fma_f32 v[76:77], v[76:77], v[218:219], v[156:157]
	v_lshlrev_b32_e32 v68, 16, v69
	v_and_b32_e32 v69, 0xffff0000, v69
	v_pk_fma_f32 v[78:79], v[78:79], v[68:69], v[158:159]
	s_nop 0
	global_store_dwordx4 v[224:225], v[76:79], off
	s_waitcnt vmcnt(7)
	v_lshlrev_b32_e32 v218, 16, v70
	v_and_b32_e32 v219, 0xffff0000, v70
	v_pk_fma_f32 v[194:195], v[194:195], v[218:219], v[166:167]
	v_lshlrev_b32_e32 v70, 16, v71
	v_and_b32_e32 v71, 0xffff0000, v71
	v_pk_fma_f32 v[196:197], v[196:197], v[70:71], v[168:169]
	s_nop 0
	global_store_dwordx4 v[224:225], v[194:197], off offset:64
	s_waitcnt vmcnt(7)
	v_lshlrev_b32_e32 v218, 16, v72
	v_and_b32_e32 v219, 0xffff0000, v72
	v_pk_fma_f32 v[198:199], v[198:199], v[218:219], v[178:179]
	v_lshlrev_b32_e32 v72, 16, v73
	v_and_b32_e32 v73, 0xffff0000, v73
	v_pk_fma_f32 v[200:201], v[200:201], v[72:73], v[180:181]
	s_nop 0
	global_store_dwordx4 v[224:225], v[198:201], off offset:128
	s_waitcnt vmcnt(7)
	v_lshlrev_b32_e32 v218, 16, v74
	v_and_b32_e32 v219, 0xffff0000, v74
	v_pk_fma_f32 v[64:65], v[64:65], v[218:219], v[182:183]
	v_lshlrev_b32_e32 v74, 16, v75
	v_and_b32_e32 v75, 0xffff0000, v75
	v_pk_fma_f32 v[66:67], v[66:67], v[74:75], v[184:185]
	s_nop 0
	global_store_dwordx4 v[224:225], v[64:67], off offset:192
	v_add_u32_e32 v232, 0x20000, v228
	v_lshl_add_u64 v[222:223], v[232:233], 0, s[4:5]
	global_load_dwordx4 v[156:159], v[222:223], off
	global_load_dwordx4 v[166:169], v[222:223], off offset:64
	global_load_dwordx4 v[178:181], v[222:223], off offset:128
	global_load_dwordx4 v[182:185], v[222:223], off offset:192
	v_add_u32_e32 v232, 0x10000, v228
	v_lshl_add_u64 v[224:225], v[232:233], 0, s[4:5]
	s_waitcnt vmcnt(11)
	v_lshlrev_b32_e32 v218, 16, v106
	v_and_b32_e32 v219, 0xffff0000, v106
	v_pk_fma_f32 v[60:61], v[60:61], v[218:219], v[186:187]
	v_lshlrev_b32_e32 v106, 16, v107
	v_and_b32_e32 v107, 0xffff0000, v107
	v_pk_fma_f32 v[62:63], v[62:63], v[106:107], v[188:189]
	s_nop 0
	global_store_dwordx4 v[224:225], v[60:63], off
	s_waitcnt vmcnt(11)
	v_lshlrev_b32_e32 v218, 16, v108
	v_and_b32_e32 v219, 0xffff0000, v108
	v_pk_fma_f32 v[56:57], v[56:57], v[218:219], v[190:191]
	v_lshlrev_b32_e32 v108, 16, v109
	v_and_b32_e32 v109, 0xffff0000, v109
	v_pk_fma_f32 v[58:59], v[58:59], v[108:109], v[192:193]
	s_nop 0
	global_store_dwordx4 v[224:225], v[56:59], off offset:64
	s_waitcnt vmcnt(11)
	v_lshlrev_b32_e32 v218, 16, v110
	v_and_b32_e32 v219, 0xffff0000, v110
	v_pk_fma_f32 v[52:53], v[52:53], v[218:219], v[210:211]
	v_lshlrev_b32_e32 v110, 16, v111
	v_and_b32_e32 v111, 0xffff0000, v111
	v_pk_fma_f32 v[54:55], v[54:55], v[110:111], v[212:213]
	s_nop 0
	global_store_dwordx4 v[224:225], v[52:55], off offset:128
	s_waitcnt vmcnt(11)
	v_lshlrev_b32_e32 v218, 16, v112
	v_and_b32_e32 v219, 0xffff0000, v112
	v_pk_fma_f32 v[48:49], v[48:49], v[218:219], v[214:215]
	v_lshlrev_b32_e32 v112, 16, v113
	v_and_b32_e32 v113, 0xffff0000, v113
	v_pk_fma_f32 v[50:51], v[50:51], v[112:113], v[216:217]
	s_nop 0
	global_store_dwordx4 v[224:225], v[48:51], off offset:192
	v_add_u32_e32 v232, 0x30000, v228
	v_lshl_add_u64 v[222:223], v[232:233], 0, s[4:5]
	global_load_dwordx4 v[186:189], v[222:223], off
	global_load_dwordx4 v[190:193], v[222:223], off offset:64
	global_load_dwordx4 v[210:213], v[222:223], off offset:128
	global_load_dwordx4 v[214:217], v[222:223], off offset:192
	v_add_u32_e32 v232, 0x40000, v228
	v_lshl_add_u64 v[222:223], v[232:233], 0, s[4:5]
	global_load_dwordx4 v[68:71], v[222:223], off
	global_load_dwordx4 v[72:75], v[222:223], off offset:64
	global_load_dwordx4 v[106:109], v[222:223], off offset:128
	global_load_dwordx4 v[110:113], v[222:223], off offset:192
	v_add_u32_e32 v232, 0x20000, v228
	v_lshl_add_u64 v[224:225], v[232:233], 0, s[4:5]
	s_waitcnt vmcnt(15)
	v_lshlrev_b32_e32 v218, 16, v114
	v_and_b32_e32 v219, 0xffff0000, v114
	v_pk_fma_f32 v[44:45], v[44:45], v[218:219], v[156:157]
	v_lshlrev_b32_e32 v114, 16, v115
	v_and_b32_e32 v115, 0xffff0000, v115
	v_pk_fma_f32 v[46:47], v[46:47], v[114:115], v[158:159]
	s_nop 0
	global_store_dwordx4 v[224:225], v[44:47], off
	s_waitcnt vmcnt(15)
	v_lshlrev_b32_e32 v218, 16, v202
	v_and_b32_e32 v219, 0xffff0000, v202
	v_pk_fma_f32 v[40:41], v[40:41], v[218:219], v[166:167]
	v_lshlrev_b32_e32 v202, 16, v203
	v_and_b32_e32 v203, 0xffff0000, v203
	v_pk_fma_f32 v[42:43], v[42:43], v[202:203], v[168:169]
	s_nop 0
	global_store_dwordx4 v[224:225], v[40:43], off offset:64
	s_waitcnt vmcnt(15)
	v_lshlrev_b32_e32 v218, 16, v226
	v_and_b32_e32 v219, 0xffff0000, v226
	v_pk_fma_f32 v[36:37], v[36:37], v[218:219], v[178:179]
	v_lshlrev_b32_e32 v226, 16, v227
	v_and_b32_e32 v227, 0xffff0000, v227
	v_pk_fma_f32 v[38:39], v[38:39], v[226:227], v[180:181]
	s_nop 0
	global_store_dwordx4 v[224:225], v[36:39], off offset:128
	s_waitcnt vmcnt(15)
	v_lshlrev_b32_e32 v218, 16, v246
	v_and_b32_e32 v219, 0xffff0000, v246
	v_pk_fma_f32 v[32:33], v[32:33], v[218:219], v[182:183]
	v_lshlrev_b32_e32 v246, 16, v247
	v_and_b32_e32 v247, 0xffff0000, v247
	v_pk_fma_f32 v[34:35], v[34:35], v[246:247], v[184:185]
	s_nop 0
	global_store_dwordx4 v[224:225], v[32:35], off offset:192
	v_add_u32_e32 v232, 0x30000, v228
	v_lshl_add_u64 v[224:225], v[232:233], 0, s[4:5]
	s_waitcnt vmcnt(11)
	v_lshlrev_b32_e32 v218, 16, v248
	v_and_b32_e32 v219, 0xffff0000, v248
	v_pk_fma_f32 v[28:29], v[28:29], v[218:219], v[186:187]
	v_lshlrev_b32_e32 v248, 16, v249
	v_and_b32_e32 v249, 0xffff0000, v249
	v_pk_fma_f32 v[30:31], v[30:31], v[248:249], v[188:189]
	s_nop 0
	global_store_dwordx4 v[224:225], v[28:31], off
	s_waitcnt vmcnt(11)
	v_lshlrev_b32_e32 v218, 16, v242
	v_and_b32_e32 v219, 0xffff0000, v242
	v_pk_fma_f32 v[24:25], v[24:25], v[218:219], v[190:191]
	v_lshlrev_b32_e32 v242, 16, v243
	v_and_b32_e32 v243, 0xffff0000, v243
	v_pk_fma_f32 v[26:27], v[26:27], v[242:243], v[192:193]
	s_nop 0
	global_store_dwordx4 v[224:225], v[24:27], off offset:64
	s_waitcnt vmcnt(11)
	v_lshlrev_b32_e32 v218, 16, v244
	v_and_b32_e32 v219, 0xffff0000, v244
	v_pk_fma_f32 v[20:21], v[20:21], v[218:219], v[210:211]
	v_lshlrev_b32_e32 v244, 16, v245
	v_and_b32_e32 v245, 0xffff0000, v245
	v_pk_fma_f32 v[22:23], v[22:23], v[244:245], v[212:213]
	s_nop 0
	global_store_dwordx4 v[224:225], v[20:23], off offset:128
	s_waitcnt vmcnt(11)
	v_lshlrev_b32_e32 v218, 16, v238
	v_and_b32_e32 v219, 0xffff0000, v238
	v_pk_fma_f32 v[16:17], v[16:17], v[218:219], v[214:215]
	v_lshlrev_b32_e32 v238, 16, v239
	v_and_b32_e32 v239, 0xffff0000, v239
	v_pk_fma_f32 v[18:19], v[18:19], v[238:239], v[216:217]
	s_nop 0
	global_store_dwordx4 v[224:225], v[16:19], off offset:192
	v_add_u32_e32 v232, 0x40000, v228
	v_lshl_add_u64 v[224:225], v[232:233], 0, s[4:5]
	s_waitcnt vmcnt(11)
	v_lshlrev_b32_e32 v218, 16, v240
	v_and_b32_e32 v219, 0xffff0000, v240
	v_pk_fma_f32 v[12:13], v[12:13], v[218:219], v[68:69]
	v_lshlrev_b32_e32 v240, 16, v241
	v_and_b32_e32 v241, 0xffff0000, v241
	v_pk_fma_f32 v[14:15], v[14:15], v[240:241], v[70:71]
	s_nop 0
	global_store_dwordx4 v[224:225], v[12:15], off
	s_waitcnt vmcnt(11)
	v_lshlrev_b32_e32 v218, 16, v234
	v_and_b32_e32 v219, 0xffff0000, v234
	v_pk_fma_f32 v[8:9], v[8:9], v[218:219], v[72:73]
	v_lshlrev_b32_e32 v234, 16, v235
	v_and_b32_e32 v235, 0xffff0000, v235
	v_pk_fma_f32 v[10:11], v[10:11], v[234:235], v[74:75]
	s_nop 0
	global_store_dwordx4 v[224:225], v[8:11], off offset:64
	s_waitcnt vmcnt(11)
	v_lshlrev_b32_e32 v218, 16, v236
	v_and_b32_e32 v219, 0xffff0000, v236
	v_pk_fma_f32 v[4:5], v[4:5], v[218:219], v[106:107]
	v_lshlrev_b32_e32 v236, 16, v237
	v_and_b32_e32 v237, 0xffff0000, v237
	v_pk_fma_f32 v[6:7], v[6:7], v[236:237], v[108:109]
	s_nop 0
	global_store_dwordx4 v[224:225], v[4:7], off offset:128
	s_waitcnt vmcnt(11)
	v_lshlrev_b32_e32 v218, 16, v230
	v_and_b32_e32 v219, 0xffff0000, v230
	v_pk_fma_f32 v[0:1], v[0:1], v[218:219], v[110:111]
	v_lshlrev_b32_e32 v230, 16, v231
	v_and_b32_e32 v231, 0xffff0000, v231
	v_pk_fma_f32 v[2:3], v[2:3], v[230:231], v[112:113]
	s_nop 0
	global_store_dwordx4 v[224:225], v[0:3], off offset:192
	s_nop 1
	v_lshl_add_u64 v[0:1], v[102:103], 0, v[96:97]
	v_lshl_add_u64 v[2:3], v[0:1], 0, s[36:37]
	s_mov_b64 s[36:37], 0x65000
	global_load_lds_dwordx4 v[2:3], off
	v_lshl_add_u64 v[2:3], v[0:1], 0, s[36:37]
	s_mov_b32 m0, s11
	s_mov_b64 s[36:37], 0xc9000
	v_readfirstlane_b32 s11, v132
	global_load_lds_dwordx4 v[2:3], off
	v_lshl_add_u64 v[2:3], v[0:1], 0, s[36:37]
	s_mov_b32 m0, s11
	s_mov_b64 s[36:37], 0x12d000
	v_readfirstlane_b32 s11, v131
	global_load_lds_dwordx4 v[2:3], off
	v_lshl_add_u64 v[2:3], v[0:1], 0, s[36:37]
	s_mov_b32 m0, s11
	s_mov_b64 s[36:37], 0x191000
	v_readfirstlane_b32 s11, v130
	global_load_lds_dwordx4 v[2:3], off
	v_lshl_add_u64 v[0:1], v[0:1], 0, s[36:37]
	s_mov_b32 m0, s11
	s_nop 0
	global_load_lds_dwordx4 v[0:1], off
	v_lshl_add_u64 v[0:1], v[88:89], 0, s[8:9]
	v_readfirstlane_b32 s8, v129
	s_mov_b32 m0, s8
	v_readfirstlane_b32 s8, v128
	global_load_lds_dwordx4 v[0:1], off
	v_lshl_add_u64 v[2:3], v[0:1], 0, s[40:41]
	s_mov_b32 m0, s8
	s_mov_b64 s[8:9], 0x20000
	global_load_lds_dwordx4 v[2:3], off
	v_lshl_add_u64 v[2:3], v[0:1], 0, s[8:9]
	v_readfirstlane_b32 s8, v127
	s_mov_b32 m0, s8
	s_mov_b64 s[8:9], 0x30000
	v_lshl_add_u64 v[0:1], v[0:1], 0, s[8:9]
	v_readfirstlane_b32 s8, v126
	global_load_lds_dwordx4 v[2:3], off
	s_mov_b32 m0, s8
	s_mov_b64 s[8:9], 0
	global_load_lds_dwordx4 v[0:1], off
	s_nop 0
	v_mov_b32_e32 v0, 0
	v_mov_b32_e32 v1, v0
	v_mov_b32_e32 v2, v0
	v_mov_b32_e32 v3, v0
	v_mov_b32_e32 v4, v0
	v_mov_b32_e32 v5, v0
	v_mov_b32_e32 v6, v0
	v_mov_b32_e32 v7, v0
	v_mov_b32_e32 v8, v0
	v_mov_b32_e32 v9, v0
	v_mov_b32_e32 v10, v0
	v_mov_b32_e32 v11, v0
	v_mov_b32_e32 v12, v0
	v_mov_b32_e32 v13, v0
	v_mov_b32_e32 v14, v0
	v_mov_b32_e32 v15, v0
	v_mov_b32_e32 v16, v0
	v_mov_b32_e32 v17, v0
	v_mov_b32_e32 v18, v0
	v_mov_b32_e32 v19, v0
	v_mov_b32_e32 v20, v0
	v_mov_b32_e32 v21, v0
	v_mov_b32_e32 v22, v0
	v_mov_b32_e32 v23, v0
	v_mov_b32_e32 v24, v0
	v_mov_b32_e32 v25, v0
	v_mov_b32_e32 v26, v0
	v_mov_b32_e32 v27, v0
	v_mov_b32_e32 v28, v0
	v_mov_b32_e32 v29, v0
	v_mov_b32_e32 v30, v0
	v_mov_b32_e32 v31, v0
	v_mov_b32_e32 v32, v0
	v_mov_b32_e32 v33, v0
	v_mov_b32_e32 v34, v0
	v_mov_b32_e32 v35, v0
	v_mov_b32_e32 v36, v0
	v_mov_b32_e32 v37, v0
	v_mov_b32_e32 v38, v0
	v_mov_b32_e32 v39, v0
	v_mov_b32_e32 v40, v0
	v_mov_b32_e32 v41, v0
	v_mov_b32_e32 v42, v0
	v_mov_b32_e32 v43, v0
	v_mov_b32_e32 v44, v0
	v_mov_b32_e32 v45, v0
	v_mov_b32_e32 v46, v0
	v_mov_b32_e32 v47, v0
	v_mov_b32_e32 v48, v0
	v_mov_b32_e32 v49, v0
	v_mov_b32_e32 v50, v0
	v_mov_b32_e32 v51, v0
	v_mov_b32_e32 v52, v0
	v_mov_b32_e32 v53, v0
	v_mov_b32_e32 v54, v0
	v_mov_b32_e32 v55, v0
	v_mov_b32_e32 v56, v0
	v_mov_b32_e32 v57, v0
	v_mov_b32_e32 v58, v0
	v_mov_b32_e32 v59, v0
	v_mov_b32_e32 v60, v0
	v_mov_b32_e32 v61, v0
	v_mov_b32_e32 v62, v0
	v_mov_b32_e32 v63, v0
	v_mov_b32_e32 v64, v0
	v_mov_b32_e32 v65, v0
	v_mov_b32_e32 v66, v0
	v_mov_b32_e32 v67, v0
	v_mov_b32_e32 v68, v0
	v_mov_b32_e32 v69, v0
	v_mov_b32_e32 v70, v0
	v_mov_b32_e32 v71, v0
	v_mov_b32_e32 v72, v0
	v_mov_b32_e32 v73, v0
	v_mov_b32_e32 v74, v0
	v_mov_b32_e32 v75, v0
	v_mov_b32_e32 v76, v0
	v_mov_b32_e32 v77, v0
	v_mov_b32_e32 v78, v0
	v_mov_b32_e32 v79, v0
	s_nop 0
	s_nop 0
	s_mov_b32 s35, 0x9000
	v_add_u32_e32 v204, s35, v81
	v_lshl_add_u64 v[202:203], v[94:95], 0, s[8:9]
	s_mov_b64 s[36:37], 0x6182080
	v_readfirstlane_b32 s35, v204
	v_add_u32_e32 v228, 0x1000, v204
	v_lshl_add_u64 v[210:211], v[202:203], 0, s[36:37]
	s_mov_b32 m0, s35
	s_mov_b64 s[36:37], 0x61e6080
	v_readfirstlane_b32 s35, v228
	v_add_u32_e32 v228, 0x2000, v204
	global_load_lds_dwordx4 v[210:211], off
	v_lshl_add_u64 v[210:211], v[202:203], 0, s[36:37]
	s_mov_b32 m0, s35
	s_mov_b64 s[36:37], 0x624a080
	v_readfirstlane_b32 s35, v228
	v_add_u32_e32 v228, 0x3000, v204
	global_load_lds_dwordx4 v[210:211], off
	v_lshl_add_u64 v[210:211], v[202:203], 0, s[36:37]
	s_mov_b32 m0, s35
	s_mov_b64 s[36:37], 0x62ae080
	v_readfirstlane_b32 s35, v228
	global_load_lds_dwordx4 v[210:211], off
	v_lshl_add_u64 v[210:211], v[202:203], 0, s[36:37]
	s_mov_b32 m0, s35
	s_mov_b64 s[36:37], 0x6312080
	global_load_lds_dwordx4 v[210:211], off
	v_add_u32_e32 v210, 0x4000, v204
	v_lshl_add_u64 v[202:203], v[202:203], 0, s[36:37]
	v_readfirstlane_b32 s35, v210
	s_mov_b32 m0, s35
	v_add_u32_e32 v228, 0x5000, v204
	global_load_lds_dwordx4 v[202:203], off
	v_lshl_add_u64 v[202:203], v[100:101], 0, s[8:9]
	s_mov_b64 s[36:37], 0x14931080
	v_readfirstlane_b32 s35, v228
	v_add_u32_e32 v228, 0x6000, v204
	v_lshl_add_u64 v[210:211], v[202:203], 0, s[36:37]
	s_mov_b32 m0, s35
	s_mov_b64 s[36:37], 0x14941080
	v_readfirstlane_b32 s35, v228
	v_add_u32_e32 v228, 0x7000, v204
	global_load_lds_dwordx4 v[210:211], off
	v_lshl_add_u64 v[210:211], v[202:203], 0, s[36:37]
	s_mov_b32 m0, s35
	s_mov_b64 s[36:37], 0x14951080
	v_readfirstlane_b32 s35, v228
	v_add_u32_e32 v204, 0x8000, v204
	global_load_lds_dwordx4 v[210:211], off
	v_lshl_add_u64 v[210:211], v[202:203], 0, s[36:37]
	s_mov_b32 m0, s35
	s_mov_b64 s[36:37], 0x14961080
	v_readfirstlane_b32 s35, v204
	global_load_lds_dwordx4 v[210:211], off
	v_lshl_add_u64 v[202:203], v[202:203], 0, s[36:37]
	s_mov_b32 m0, s35
	s_nop 0
	global_load_lds_dwordx4 v[202:203], off
	s_waitcnt vmcnt(9) lgkmcnt(0)
	s_barrier
.LBB0_90:
	s_add_i32 s11, s10, 1
	s_bitcmp1_b32 s10, 0
	s_cselect_b32 s10, 0x9000, 0
	s_add_i32 s10, s10, 0
	v_add_u32_e32 v96, s10, v116
	v_add_u32_e32 v114, v96, v117
	ds_read_b128 v[102:105], v114
	ds_read_b128 v[106:109], v114 offset:2048
	ds_read_b128 v[110:113], v114 offset:4096
	ds_read_b128 v[126:129], v114 offset:6144
	v_add_u32_e32 v96, v96, v118
	ds_read_b128 v[130:133], v114 offset:8192
	ds_read_b128 v[156:159], v96 offset:20480
	ds_read_b128 v[166:169], v96 offset:22528
	ds_read_b128 v[178:181], v96 offset:24576
	ds_read_b128 v[182:185], v96 offset:26624
	v_add_u32_e32 v210, s10, v119
	v_add_u32_e32 v211, v210, v117
	ds_read_b128 v[212:215], v211
	ds_read_b128 v[216:219], v211 offset:2048
	ds_read_b128 v[220:223], v211 offset:4096
	ds_read_b128 v[224:227], v211 offset:6144
	v_add_u32_e32 v228, v210, v118
	ds_read_b128 v[230:233], v211 offset:8192
	ds_read_b128 v[234:237], v228 offset:20480
	ds_read_b128 v[238:241], v228 offset:22528
	ds_read_b128 v[242:245], v228 offset:24576
	ds_read_b128 v[246:249], v228 offset:26624
	s_setprio 1
	s_waitcnt lgkmcnt(9)
	v_mfma_f32_16x16x32_bf16 v[76:79], v[156:159], v[102:105], v[76:79]
	v_mfma_f32_16x16x32_bf16 v[72:75], v[166:169], v[102:105], v[72:75]
	v_mfma_f32_16x16x32_bf16 v[68:71], v[178:181], v[102:105], v[68:71]
	v_mfma_f32_16x16x32_bf16 v[64:67], v[182:185], v[102:105], v[64:67]
	v_mfma_f32_16x16x32_bf16 v[60:63], v[156:159], v[106:109], v[60:63]
	v_mfma_f32_16x16x32_bf16 v[56:59], v[166:169], v[106:109], v[56:59]
	v_mfma_f32_16x16x32_bf16 v[52:55], v[178:181], v[106:109], v[52:55]
	v_mfma_f32_16x16x32_bf16 v[48:51], v[182:185], v[106:109], v[48:51]
	v_mfma_f32_16x16x32_bf16 v[44:47], v[156:159], v[110:113], v[44:47]
	v_mfma_f32_16x16x32_bf16 v[40:43], v[166:169], v[110:113], v[40:43]
	v_mfma_f32_16x16x32_bf16 v[36:39], v[178:181], v[110:113], v[36:39]
	v_mfma_f32_16x16x32_bf16 v[32:35], v[182:185], v[110:113], v[32:35]
	v_mfma_f32_16x16x32_bf16 v[28:31], v[156:159], v[126:129], v[28:31]
	v_mfma_f32_16x16x32_bf16 v[24:27], v[166:169], v[126:129], v[24:27]
	v_mfma_f32_16x16x32_bf16 v[20:23], v[178:181], v[126:129], v[20:23]
	v_mfma_f32_16x16x32_bf16 v[16:19], v[182:185], v[126:129], v[16:19]
	v_mfma_f32_16x16x32_bf16 v[12:15], v[156:159], v[130:133], v[12:15]
	v_mfma_f32_16x16x32_bf16 v[8:11], v[166:169], v[130:133], v[8:11]
	v_mfma_f32_16x16x32_bf16 v[4:7], v[178:181], v[130:133], v[4:7]
	v_mfma_f32_16x16x32_bf16 v[0:3], v[182:185], v[130:133], v[0:3]
	s_setprio 0
	s_setprio 1
	s_waitcnt lgkmcnt(0)
	s_setprio 0
	s_barrier
	s_add_u32 s8, s8, 0x80
	s_addc_u32 s9, s9, 0
	s_mov_b32 s35, s10
	v_add_u32_e32 v204, s35, v81
	v_lshl_add_u64 v[202:203], v[94:95], 0, s[8:9]
	s_mov_b64 s[36:37], 0x6182080
	v_readfirstlane_b32 s35, v204
	v_add_u32_e32 v228, 0x1000, v204
	v_lshl_add_u64 v[210:211], v[202:203], 0, s[36:37]
	s_mov_b32 m0, s35
	s_mov_b64 s[36:37], 0x61e6080
	v_readfirstlane_b32 s35, v228
	v_add_u32_e32 v228, 0x2000, v204
	global_load_lds_dwordx4 v[210:211], off
	v_lshl_add_u64 v[210:211], v[202:203], 0, s[36:37]
	s_mov_b32 m0, s35
	s_mov_b64 s[36:37], 0x624a080
	v_readfirstlane_b32 s35, v228
	v_add_u32_e32 v228, 0x3000, v204
	global_load_lds_dwordx4 v[210:211], off
	v_lshl_add_u64 v[210:211], v[202:203], 0, s[36:37]
	s_mov_b32 m0, s35
	s_mov_b64 s[36:37], 0x62ae080
	v_readfirstlane_b32 s35, v228
	global_load_lds_dwordx4 v[210:211], off
	v_lshl_add_u64 v[210:211], v[202:203], 0, s[36:37]
	s_mov_b32 m0, s35
	s_mov_b64 s[36:37], 0x6312080
	global_load_lds_dwordx4 v[210:211], off
	v_add_u32_e32 v210, 0x4000, v204
	v_lshl_add_u64 v[202:203], v[202:203], 0, s[36:37]
	v_readfirstlane_b32 s35, v210
	s_mov_b32 m0, s35
	v_add_u32_e32 v228, 0x5000, v204
	global_load_lds_dwordx4 v[202:203], off
	v_lshl_add_u64 v[202:203], v[100:101], 0, s[8:9]
	s_mov_b64 s[36:37], 0x14931080
	v_readfirstlane_b32 s35, v228
	v_add_u32_e32 v228, 0x6000, v204
	v_lshl_add_u64 v[210:211], v[202:203], 0, s[36:37]
	s_mov_b32 m0, s35
	s_mov_b64 s[36:37], 0x14941080
	v_readfirstlane_b32 s35, v228
	v_add_u32_e32 v228, 0x7000, v204
	global_load_lds_dwordx4 v[210:211], off
	v_lshl_add_u64 v[210:211], v[202:203], 0, s[36:37]
	s_mov_b32 m0, s35
	s_mov_b64 s[36:37], 0x14951080
	v_readfirstlane_b32 s35, v228
	v_add_u32_e32 v204, 0x8000, v204
	global_load_lds_dwordx4 v[210:211], off
	v_lshl_add_u64 v[210:211], v[202:203], 0, s[36:37]
	s_mov_b32 m0, s35
	s_mov_b64 s[36:37], 0x14961080
	v_readfirstlane_b32 s35, v204
	global_load_lds_dwordx4 v[210:211], off
	v_lshl_add_u64 v[202:203], v[202:203], 0, s[36:37]
	s_mov_b32 m0, s35
	s_nop 0
	global_load_lds_dwordx4 v[202:203], off
	s_setprio 1
	v_mfma_f32_16x16x32_bf16 v[76:79], v[234:237], v[212:215], v[76:79]
	v_mfma_f32_16x16x32_bf16 v[72:75], v[238:241], v[212:215], v[72:75]
	v_mfma_f32_16x16x32_bf16 v[68:71], v[242:245], v[212:215], v[68:71]
	v_mfma_f32_16x16x32_bf16 v[64:67], v[246:249], v[212:215], v[64:67]
	v_mfma_f32_16x16x32_bf16 v[60:63], v[234:237], v[216:219], v[60:63]
	v_mfma_f32_16x16x32_bf16 v[56:59], v[238:241], v[216:219], v[56:59]
	v_mfma_f32_16x16x32_bf16 v[52:55], v[242:245], v[216:219], v[52:55]
	v_mfma_f32_16x16x32_bf16 v[48:51], v[246:249], v[216:219], v[48:51]
	v_mfma_f32_16x16x32_bf16 v[44:47], v[234:237], v[220:223], v[44:47]
	v_mfma_f32_16x16x32_bf16 v[40:43], v[238:241], v[220:223], v[40:43]
	v_mfma_f32_16x16x32_bf16 v[36:39], v[242:245], v[220:223], v[36:39]
	v_mfma_f32_16x16x32_bf16 v[32:35], v[246:249], v[220:223], v[32:35]
	v_mfma_f32_16x16x32_bf16 v[28:31], v[234:237], v[224:227], v[28:31]
	v_mfma_f32_16x16x32_bf16 v[24:27], v[238:241], v[224:227], v[24:27]
	v_mfma_f32_16x16x32_bf16 v[20:23], v[242:245], v[224:227], v[20:23]
	v_mfma_f32_16x16x32_bf16 v[16:19], v[246:249], v[224:227], v[16:19]
	v_mfma_f32_16x16x32_bf16 v[12:15], v[234:237], v[230:233], v[12:15]
	v_mfma_f32_16x16x32_bf16 v[8:11], v[238:241], v[230:233], v[8:11]
	v_mfma_f32_16x16x32_bf16 v[4:7], v[242:245], v[230:233], v[4:7]
	v_mfma_f32_16x16x32_bf16 v[0:3], v[246:249], v[230:233], v[0:3]
	s_setprio 0
	s_cmpk_lg_i32 s8, 0x700
	s_mov_b32 s10, s11
	s_waitcnt vmcnt(9)
	s_barrier
	s_cbranch_scc1 .LBB0_90
	s_add_i32 s11, s10, 1
	s_bitcmp1_b32 s10, 0
	s_cselect_b32 s10, 0x9000, 0
	s_add_i32 s10, s10, 0
	v_add_u32_e32 v96, s10, v116
	v_add_u32_e32 v114, v96, v117
	ds_read_b128 v[102:105], v114
	ds_read_b128 v[106:109], v114 offset:2048
	ds_read_b128 v[110:113], v114 offset:4096
	ds_read_b128 v[126:129], v114 offset:6144
	v_add_u32_e32 v96, v96, v118
	ds_read_b128 v[130:133], v114 offset:8192
	ds_read_b128 v[156:159], v96 offset:20480
	ds_read_b128 v[166:169], v96 offset:22528
	ds_read_b128 v[178:181], v96 offset:24576
	ds_read_b128 v[182:185], v96 offset:26624
	v_add_u32_e32 v210, s10, v119
	v_add_u32_e32 v211, v210, v117
	ds_read_b128 v[212:215], v211
	ds_read_b128 v[216:219], v211 offset:2048
	ds_read_b128 v[220:223], v211 offset:4096
	ds_read_b128 v[224:227], v211 offset:6144
	v_add_u32_e32 v228, v210, v118
	ds_read_b128 v[230:233], v211 offset:8192
	ds_read_b128 v[234:237], v228 offset:20480
	ds_read_b128 v[238:241], v228 offset:22528
	ds_read_b128 v[242:245], v228 offset:24576
	ds_read_b128 v[246:249], v228 offset:26624
	s_setprio 1
	s_waitcnt lgkmcnt(9)
	v_mfma_f32_16x16x32_bf16 v[76:79], v[156:159], v[102:105], v[76:79]
	v_mfma_f32_16x16x32_bf16 v[72:75], v[166:169], v[102:105], v[72:75]
	v_mfma_f32_16x16x32_bf16 v[68:71], v[178:181], v[102:105], v[68:71]
	v_mfma_f32_16x16x32_bf16 v[64:67], v[182:185], v[102:105], v[64:67]
	v_mfma_f32_16x16x32_bf16 v[60:63], v[156:159], v[106:109], v[60:63]
	v_mfma_f32_16x16x32_bf16 v[56:59], v[166:169], v[106:109], v[56:59]
	v_mfma_f32_16x16x32_bf16 v[52:55], v[178:181], v[106:109], v[52:55]
	v_mfma_f32_16x16x32_bf16 v[48:51], v[182:185], v[106:109], v[48:51]
	v_mfma_f32_16x16x32_bf16 v[44:47], v[156:159], v[110:113], v[44:47]
	v_mfma_f32_16x16x32_bf16 v[40:43], v[166:169], v[110:113], v[40:43]
	v_mfma_f32_16x16x32_bf16 v[36:39], v[178:181], v[110:113], v[36:39]
	v_mfma_f32_16x16x32_bf16 v[32:35], v[182:185], v[110:113], v[32:35]
	v_mfma_f32_16x16x32_bf16 v[28:31], v[156:159], v[126:129], v[28:31]
	v_mfma_f32_16x16x32_bf16 v[24:27], v[166:169], v[126:129], v[24:27]
	v_mfma_f32_16x16x32_bf16 v[20:23], v[178:181], v[126:129], v[20:23]
	v_mfma_f32_16x16x32_bf16 v[16:19], v[182:185], v[126:129], v[16:19]
	v_mfma_f32_16x16x32_bf16 v[12:15], v[156:159], v[130:133], v[12:15]
	v_mfma_f32_16x16x32_bf16 v[8:11], v[166:169], v[130:133], v[8:11]
	v_mfma_f32_16x16x32_bf16 v[4:7], v[178:181], v[130:133], v[4:7]
	v_mfma_f32_16x16x32_bf16 v[0:3], v[182:185], v[130:133], v[0:3]
	s_setprio 0
	s_setprio 1
	s_waitcnt lgkmcnt(0)
	v_mfma_f32_16x16x32_bf16 v[76:79], v[234:237], v[212:215], v[76:79]
	v_mfma_f32_16x16x32_bf16 v[72:75], v[238:241], v[212:215], v[72:75]
	v_mfma_f32_16x16x32_bf16 v[68:71], v[242:245], v[212:215], v[68:71]
	v_mfma_f32_16x16x32_bf16 v[64:67], v[246:249], v[212:215], v[64:67]
	v_mfma_f32_16x16x32_bf16 v[60:63], v[234:237], v[216:219], v[60:63]
	v_mfma_f32_16x16x32_bf16 v[56:59], v[238:241], v[216:219], v[56:59]
	v_mfma_f32_16x16x32_bf16 v[52:55], v[242:245], v[216:219], v[52:55]
	v_mfma_f32_16x16x32_bf16 v[48:51], v[246:249], v[216:219], v[48:51]
	v_mfma_f32_16x16x32_bf16 v[44:47], v[234:237], v[220:223], v[44:47]
	v_mfma_f32_16x16x32_bf16 v[40:43], v[238:241], v[220:223], v[40:43]
	v_mfma_f32_16x16x32_bf16 v[36:39], v[242:245], v[220:223], v[36:39]
	v_mfma_f32_16x16x32_bf16 v[32:35], v[246:249], v[220:223], v[32:35]
	v_mfma_f32_16x16x32_bf16 v[28:31], v[234:237], v[224:227], v[28:31]
	v_mfma_f32_16x16x32_bf16 v[24:27], v[238:241], v[224:227], v[24:27]
	v_mfma_f32_16x16x32_bf16 v[20:23], v[242:245], v[224:227], v[20:23]
	v_mfma_f32_16x16x32_bf16 v[16:19], v[246:249], v[224:227], v[16:19]
	v_mfma_f32_16x16x32_bf16 v[12:15], v[234:237], v[230:233], v[12:15]
	v_mfma_f32_16x16x32_bf16 v[8:11], v[238:241], v[230:233], v[8:11]
	v_mfma_f32_16x16x32_bf16 v[4:7], v[242:245], v[230:233], v[4:7]
	v_mfma_f32_16x16x32_bf16 v[0:3], v[246:249], v[230:233], v[0:3]
	s_setprio 0
	s_add_u32 s8, s8, 0x80
	s_addc_u32 s9, s9, 0
	s_mov_b32 s10, s11
	s_waitcnt vmcnt(0)
	s_barrier
	ds_read_b128 v[100:103], v122 offset:63488
	ds_read_b128 v[104:107], v122 offset:61440
	ds_read_b128 v[108:111], v122 offset:59392
	ds_read_b128 v[112:115], v122 offset:57344
	ds_read_b128 v[126:129], v123 offset:45056
	ds_read_b128 v[130:133], v123 offset:43008
	ds_read_b128 v[156:159], v123 offset:40960
	ds_read_b128 v[166:169], v123 offset:38912
	ds_read_b128 v[178:181], v123 offset:36864
	s_setprio 1
	s_waitcnt lgkmcnt(0)
	v_mfma_f32_16x16x32_bf16 v[76:79], v[112:115], v[178:181], v[76:79]
	v_mfma_f32_16x16x32_bf16 v[72:75], v[108:111], v[178:181], v[72:75]
	v_mfma_f32_16x16x32_bf16 v[68:71], v[104:107], v[178:181], v[68:71]
	v_mfma_f32_16x16x32_bf16 v[64:67], v[100:103], v[178:181], v[64:67]
	v_mfma_f32_16x16x32_bf16 v[60:63], v[112:115], v[166:169], v[60:63]
	v_mfma_f32_16x16x32_bf16 v[56:59], v[108:111], v[166:169], v[56:59]
	v_mfma_f32_16x16x32_bf16 v[52:55], v[104:107], v[166:169], v[52:55]
	v_mfma_f32_16x16x32_bf16 v[48:51], v[100:103], v[166:169], v[48:51]
	v_mfma_f32_16x16x32_bf16 v[44:47], v[112:115], v[156:159], v[44:47]
	v_mfma_f32_16x16x32_bf16 v[40:43], v[108:111], v[156:159], v[40:43]
	v_mfma_f32_16x16x32_bf16 v[36:39], v[104:107], v[156:159], v[36:39]
	v_mfma_f32_16x16x32_bf16 v[32:35], v[100:103], v[156:159], v[32:35]
	v_mfma_f32_16x16x32_bf16 v[28:31], v[112:115], v[130:133], v[28:31]
	v_mfma_f32_16x16x32_bf16 v[24:27], v[108:111], v[130:133], v[24:27]
	v_mfma_f32_16x16x32_bf16 v[20:23], v[104:107], v[130:133], v[20:23]
	v_mfma_f32_16x16x32_bf16 v[16:19], v[100:103], v[130:133], v[16:19]
	v_mfma_f32_16x16x32_bf16 v[12:15], v[112:115], v[126:129], v[12:15]
	v_mfma_f32_16x16x32_bf16 v[8:11], v[108:111], v[126:129], v[8:11]
	v_mfma_f32_16x16x32_bf16 v[4:7], v[104:107], v[126:129], v[4:7]
	v_mfma_f32_16x16x32_bf16 v[0:3], v[100:103], v[126:129], v[0:3]
	s_setprio 0
	ds_read_b128 v[100:103], v124 offset:36864
	ds_read_b128 v[104:107], v124 offset:38912
	ds_read_b128 v[108:111], v124 offset:40960
	ds_read_b128 v[112:115], v124 offset:43008
	ds_read_b128 v[126:129], v124 offset:45056
	ds_read_b128 v[130:133], v125 offset:57344
	ds_read_b128 v[156:159], v125 offset:59392
	ds_read_b128 v[166:169], v125 offset:61440
	ds_read_b128 v[122:125], v125 offset:63488
	s_setprio 1
	s_waitcnt lgkmcnt(3)
	v_mfma_f32_16x16x32_bf16 v[178:181], v[130:133], v[100:103], v[76:79]
	s_waitcnt lgkmcnt(2)
	v_mfma_f32_16x16x32_bf16 v[72:75], v[156:159], v[100:103], v[72:75]
	s_waitcnt lgkmcnt(1)
	v_mfma_f32_16x16x32_bf16 v[68:71], v[166:169], v[100:103], v[68:71]
	s_waitcnt lgkmcnt(0)
	v_mfma_f32_16x16x32_bf16 v[64:67], v[122:125], v[100:103], v[64:67]
	v_mfma_f32_16x16x32_bf16 v[60:63], v[130:133], v[104:107], v[60:63]
	v_mfma_f32_16x16x32_bf16 v[56:59], v[156:159], v[104:107], v[56:59]
	v_mfma_f32_16x16x32_bf16 v[52:55], v[166:169], v[104:107], v[52:55]
	v_mfma_f32_16x16x32_bf16 v[48:51], v[122:125], v[104:107], v[48:51]
	v_mfma_f32_16x16x32_bf16 v[44:47], v[130:133], v[108:111], v[44:47]
	v_mfma_f32_16x16x32_bf16 v[40:43], v[156:159], v[108:111], v[40:43]
	v_mfma_f32_16x16x32_bf16 v[36:39], v[166:169], v[108:111], v[36:39]
	v_mfma_f32_16x16x32_bf16 v[32:35], v[122:125], v[108:111], v[32:35]
	v_mfma_f32_16x16x32_bf16 v[28:31], v[130:133], v[112:115], v[28:31]
	v_mfma_f32_16x16x32_bf16 v[24:27], v[156:159], v[112:115], v[24:27]
	v_mfma_f32_16x16x32_bf16 v[20:23], v[166:169], v[112:115], v[20:23]
	v_mfma_f32_16x16x32_bf16 v[16:19], v[122:125], v[112:115], v[16:19]
	v_mfma_f32_16x16x32_bf16 v[12:15], v[130:133], v[126:129], v[12:15]
	v_mfma_f32_16x16x32_bf16 v[8:11], v[156:159], v[126:129], v[8:11]
	v_mfma_f32_16x16x32_bf16 v[4:7], v[166:169], v[126:129], v[4:7]
	v_mfma_f32_16x16x32_bf16 v[0:3], v[122:125], v[126:129], v[0:3]
	s_setprio 0
	v_mov_b32_e32 v76, v97
	s_waitcnt vmcnt(0)
	s_barrier
	v_ashrrev_i32_e32 v220, 7, v176
	v_mov_b32_e32 v221, 0x50
	v_and_or_b32 v224, v176, 15, s12
	v_mad_u32_u24 v224, v220, v221, v224
	v_and_b32_e32 v220, 64, v176
	v_lshrrev_b32_e32 v221, 2, v176
	v_and_b32_e32 v221, 12, v221
	v_or3_b32 v225, v220, v221, s13
	v_mul_u32_u24_e32 v216, 0x3200, v224
	v_lshl_add_u32 v216, v225, 1, v216
	v_add_u32_e32 v216, 0x2800, v216
	v_lshlrev_b32_e32 v217, 12, v224
	v_lshl_add_u32 v217, v225, 2, v217
	v_lshlrev_b32_e32 v210, 11, v224
	v_lshl_add_u32 v210, v225, 1, v210
	v_mov_b32_e32 v223, 0
	v_mov_b32_e32 v222, v216
	v_lshl_add_u64 v[224:225], v[222:223], 0, s[0:1]
	global_load_dwordx2 v[76:77], v[224:225], off
	global_load_dwordx2 v[78:79], v[224:225], off offset:32
	global_load_dwordx2 v[106:107], v[224:225], off offset:64
	global_load_dwordx2 v[108:109], v[224:225], off offset:96
	v_add_u32_e32 v222, 0x32000, v216
	v_lshl_add_u64 v[224:225], v[222:223], 0, s[0:1]
	global_load_dwordx2 v[110:111], v[224:225], off
	global_load_dwordx2 v[112:113], v[224:225], off offset:32
	global_load_dwordx2 v[122:123], v[224:225], off offset:64
	global_load_dwordx2 v[124:125], v[224:225], off offset:96
	v_add_u32_e32 v222, 0x64000, v216
	v_lshl_add_u64 v[224:225], v[222:223], 0, s[0:1]
	global_load_dwordx2 v[114:115], v[224:225], off
	global_load_dwordx2 v[226:227], v[224:225], off offset:32
	global_load_dwordx2 v[246:247], v[224:225], off offset:64
	global_load_dwordx2 v[248:249], v[224:225], off offset:96
	v_add_u32_e32 v222, 0x96000, v216
	v_lshl_add_u64 v[224:225], v[222:223], 0, s[0:1]
	global_load_dwordx2 v[242:243], v[224:225], off
	global_load_dwordx2 v[244:245], v[224:225], off offset:32
	global_load_dwordx2 v[238:239], v[224:225], off offset:64
	global_load_dwordx2 v[240:241], v[224:225], off offset:96
	v_add_u32_e32 v222, 0xc8000, v216
	v_lshl_add_u64 v[224:225], v[222:223], 0, s[0:1]
	global_load_dwordx2 v[234:235], v[224:225], off
	global_load_dwordx2 v[236:237], v[224:225], off offset:32
	global_load_dwordx2 v[230:231], v[224:225], off offset:64
	global_load_dwordx2 v[232:233], v[224:225], off offset:96
	v_mov_b32_e32 v222, v217
	v_lshl_add_u64 v[224:225], v[222:223], 0, s[4:5]
	global_load_dwordx4 v[126:129], v[224:225], off
	global_load_dwordx4 v[130:133], v[224:225], off offset:64
	global_load_dwordx4 v[156:159], v[224:225], off offset:128
	global_load_dwordx4 v[166:169], v[224:225], off offset:192
	v_add_u32_e32 v222, 0x10000, v217
	v_lshl_add_u64 v[224:225], v[222:223], 0, s[4:5]
	global_load_dwordx4 v[182:185], v[224:225], off
	global_load_dwordx4 v[186:189], v[224:225], off offset:64
	global_load_dwordx4 v[190:193], v[224:225], off offset:128
	global_load_dwordx4 v[194:197], v[224:225], off offset:192
	v_mov_b32_e32 v222, v210
	v_lshl_add_u64 v[214:215], v[222:223], 0, s[6:7]
	s_waitcnt vmcnt(7)
	v_lshlrev_b32_e32 v220, 16, v76
	v_and_b32_e32 v221, 0xffff0000, v76
	v_pk_fma_f32 v[178:179], v[178:179], v[220:221], v[126:127]
	v_lshlrev_b32_e32 v76, 16, v77
	v_and_b32_e32 v77, 0xffff0000, v77
	v_pk_fma_f32 v[180:181], v[180:181], v[76:77], v[128:129]
	s_nop 0
	v_bfe_u32 v220, v178, 16, 1
	v_add3_u32 v178, v178, v220, s33
	v_bfe_u32 v220, v179, 16, 1
	v_add3_u32 v179, v179, v220, s33
	v_bfe_u32 v220, v180, 16, 1
	v_add3_u32 v180, v180, v220, s33
	v_bfe_u32 v220, v181, 16, 1
	v_add3_u32 v181, v181, v220, s33
	v_perm_b32 v178, v179, v178, s96
	v_perm_b32 v179, v181, v180, s96
	global_store_dwordx2 v[214:215], v[178:179], off
	s_waitcnt vmcnt(7)
	v_lshlrev_b32_e32 v220, 16, v78
	v_and_b32_e32 v221, 0xffff0000, v78
	v_pk_fma_f32 v[72:73], v[72:73], v[220:221], v[130:131]
	v_lshlrev_b32_e32 v78, 16, v79
	v_and_b32_e32 v79, 0xffff0000, v79
	v_pk_fma_f32 v[74:75], v[74:75], v[78:79], v[132:133]
	s_nop 0
	v_bfe_u32 v220, v72, 16, 1
	v_add3_u32 v72, v72, v220, s33
	v_bfe_u32 v220, v73, 16, 1
	v_add3_u32 v73, v73, v220, s33
	v_bfe_u32 v220, v74, 16, 1
	v_add3_u32 v74, v74, v220, s33
	v_bfe_u32 v220, v75, 16, 1
	v_add3_u32 v75, v75, v220, s33
	v_perm_b32 v72, v73, v72, s96
	v_perm_b32 v73, v75, v74, s96
	global_store_dwordx2 v[214:215], v[72:73], off offset:32
	s_waitcnt vmcnt(7)
	v_lshlrev_b32_e32 v220, 16, v106
	v_and_b32_e32 v221, 0xffff0000, v106
	v_pk_fma_f32 v[68:69], v[68:69], v[220:221], v[156:157]
	v_lshlrev_b32_e32 v106, 16, v107
	v_and_b32_e32 v107, 0xffff0000, v107
	v_pk_fma_f32 v[70:71], v[70:71], v[106:107], v[158:159]
	s_nop 0
	v_bfe_u32 v220, v68, 16, 1
	v_add3_u32 v68, v68, v220, s33
	v_bfe_u32 v220, v69, 16, 1
	v_add3_u32 v69, v69, v220, s33
	v_bfe_u32 v220, v70, 16, 1
	v_add3_u32 v70, v70, v220, s33
	v_bfe_u32 v220, v71, 16, 1
	v_add3_u32 v71, v71, v220, s33
	v_perm_b32 v68, v69, v68, s96
	v_perm_b32 v69, v71, v70, s96
	global_store_dwordx2 v[214:215], v[68:69], off offset:64
	s_waitcnt vmcnt(7)
	v_lshlrev_b32_e32 v220, 16, v108
	v_and_b32_e32 v221, 0xffff0000, v108
	v_pk_fma_f32 v[64:65], v[64:65], v[220:221], v[166:167]
	v_lshlrev_b32_e32 v108, 16, v109
	v_and_b32_e32 v109, 0xffff0000, v109
	v_pk_fma_f32 v[66:67], v[66:67], v[108:109], v[168:169]
	s_nop 0
	v_bfe_u32 v220, v64, 16, 1
	v_add3_u32 v64, v64, v220, s33
	v_bfe_u32 v220, v65, 16, 1
	v_add3_u32 v65, v65, v220, s33
	v_bfe_u32 v220, v66, 16, 1
	v_add3_u32 v66, v66, v220, s33
	v_bfe_u32 v220, v67, 16, 1
	v_add3_u32 v67, v67, v220, s33
	v_perm_b32 v64, v65, v64, s96
	v_perm_b32 v65, v67, v66, s96
	global_store_dwordx2 v[214:215], v[64:65], off offset:96
	v_add_u32_e32 v222, 0x20000, v217
	v_lshl_add_u64 v[224:225], v[222:223], 0, s[4:5]
	global_load_dwordx4 v[126:129], v[224:225], off
	global_load_dwordx4 v[130:133], v[224:225], off offset:64
	global_load_dwordx4 v[156:159], v[224:225], off offset:128
	global_load_dwordx4 v[166:169], v[224:225], off offset:192
	v_add_u32_e32 v222, 0x8000, v210
	v_lshl_add_u64 v[214:215], v[222:223], 0, s[6:7]
	s_waitcnt vmcnt(11)
	v_lshlrev_b32_e32 v220, 16, v110
	v_and_b32_e32 v221, 0xffff0000, v110
	v_pk_fma_f32 v[60:61], v[60:61], v[220:221], v[182:183]
	v_lshlrev_b32_e32 v110, 16, v111
	v_and_b32_e32 v111, 0xffff0000, v111
	v_pk_fma_f32 v[62:63], v[62:63], v[110:111], v[184:185]
	s_nop 0
	v_bfe_u32 v220, v60, 16, 1
	v_add3_u32 v60, v60, v220, s33
	v_bfe_u32 v220, v61, 16, 1
	v_add3_u32 v61, v61, v220, s33
	v_bfe_u32 v220, v62, 16, 1
	v_add3_u32 v62, v62, v220, s33
	v_bfe_u32 v220, v63, 16, 1
	v_add3_u32 v63, v63, v220, s33
	v_perm_b32 v60, v61, v60, s96
	v_perm_b32 v61, v63, v62, s96
	global_store_dwordx2 v[214:215], v[60:61], off
	s_waitcnt vmcnt(11)
	v_lshlrev_b32_e32 v220, 16, v112
	v_and_b32_e32 v221, 0xffff0000, v112
	v_pk_fma_f32 v[56:57], v[56:57], v[220:221], v[186:187]
	v_lshlrev_b32_e32 v112, 16, v113
	v_and_b32_e32 v113, 0xffff0000, v113
	v_pk_fma_f32 v[58:59], v[58:59], v[112:113], v[188:189]
	s_nop 0
	v_bfe_u32 v220, v56, 16, 1
	v_add3_u32 v56, v56, v220, s33
	v_bfe_u32 v220, v57, 16, 1
	v_add3_u32 v57, v57, v220, s33
	v_bfe_u32 v220, v58, 16, 1
	v_add3_u32 v58, v58, v220, s33
	v_bfe_u32 v220, v59, 16, 1
	v_add3_u32 v59, v59, v220, s33
	v_perm_b32 v56, v57, v56, s96
	v_perm_b32 v57, v59, v58, s96
	global_store_dwordx2 v[214:215], v[56:57], off offset:32
	s_waitcnt vmcnt(11)
	v_lshlrev_b32_e32 v220, 16, v122
	v_and_b32_e32 v221, 0xffff0000, v122
	v_pk_fma_f32 v[52:53], v[52:53], v[220:221], v[190:191]
	v_lshlrev_b32_e32 v122, 16, v123
	v_and_b32_e32 v123, 0xffff0000, v123
	v_pk_fma_f32 v[54:55], v[54:55], v[122:123], v[192:193]
	s_nop 0
	v_bfe_u32 v220, v52, 16, 1
	v_add3_u32 v52, v52, v220, s33
	v_bfe_u32 v220, v53, 16, 1
	v_add3_u32 v53, v53, v220, s33
	v_bfe_u32 v220, v54, 16, 1
	v_add3_u32 v54, v54, v220, s33
	v_bfe_u32 v220, v55, 16, 1
	v_add3_u32 v55, v55, v220, s33
	v_perm_b32 v52, v53, v52, s96
	v_perm_b32 v53, v55, v54, s96
	global_store_dwordx2 v[214:215], v[52:53], off offset:64
	s_waitcnt vmcnt(11)
	v_lshlrev_b32_e32 v220, 16, v124
	v_and_b32_e32 v221, 0xffff0000, v124
	v_pk_fma_f32 v[48:49], v[48:49], v[220:221], v[194:195]
	v_lshlrev_b32_e32 v124, 16, v125
	v_and_b32_e32 v125, 0xffff0000, v125
	v_pk_fma_f32 v[50:51], v[50:51], v[124:125], v[196:197]
	s_nop 0
	v_bfe_u32 v220, v48, 16, 1
	v_add3_u32 v48, v48, v220, s33
	v_bfe_u32 v220, v49, 16, 1
	v_add3_u32 v49, v49, v220, s33
	v_bfe_u32 v220, v50, 16, 1
	v_add3_u32 v50, v50, v220, s33
	v_bfe_u32 v220, v51, 16, 1
	v_add3_u32 v51, v51, v220, s33
	v_perm_b32 v48, v49, v48, s96
	v_perm_b32 v49, v51, v50, s96
	global_store_dwordx2 v[214:215], v[48:49], off offset:96
	v_add_u32_e32 v222, 0x30000, v217
	v_lshl_add_u64 v[224:225], v[222:223], 0, s[4:5]
	global_load_dwordx4 v[182:185], v[224:225], off
	global_load_dwordx4 v[186:189], v[224:225], off offset:64
	global_load_dwordx4 v[190:193], v[224:225], off offset:128
	global_load_dwordx4 v[194:197], v[224:225], off offset:192
	v_add_u32_e32 v222, 0x40000, v217
	v_lshl_add_u64 v[224:225], v[222:223], 0, s[4:5]
	global_load_dwordx4 v[76:79], v[224:225], off
	global_load_dwordx4 v[106:109], v[224:225], off offset:64
	global_load_dwordx4 v[110:113], v[224:225], off offset:128
	global_load_dwordx4 v[122:125], v[224:225], off offset:192
	v_add_u32_e32 v222, 0x10000, v210
	v_lshl_add_u64 v[214:215], v[222:223], 0, s[6:7]
	s_waitcnt vmcnt(15)
	v_lshlrev_b32_e32 v220, 16, v114
	v_and_b32_e32 v221, 0xffff0000, v114
	v_pk_fma_f32 v[44:45], v[44:45], v[220:221], v[126:127]
	v_lshlrev_b32_e32 v114, 16, v115
	v_and_b32_e32 v115, 0xffff0000, v115
	v_pk_fma_f32 v[46:47], v[46:47], v[114:115], v[128:129]
	s_nop 0
	v_bfe_u32 v220, v44, 16, 1
	v_add3_u32 v44, v44, v220, s33
	v_bfe_u32 v220, v45, 16, 1
	v_add3_u32 v45, v45, v220, s33
	v_bfe_u32 v220, v46, 16, 1
	v_add3_u32 v46, v46, v220, s33
	v_bfe_u32 v220, v47, 16, 1
	v_add3_u32 v47, v47, v220, s33
	v_perm_b32 v44, v45, v44, s96
	v_perm_b32 v45, v47, v46, s96
	global_store_dwordx2 v[214:215], v[44:45], off
	s_waitcnt vmcnt(15)
	v_lshlrev_b32_e32 v220, 16, v226
	v_and_b32_e32 v221, 0xffff0000, v226
	v_pk_fma_f32 v[40:41], v[40:41], v[220:221], v[130:131]
	v_lshlrev_b32_e32 v226, 16, v227
	v_and_b32_e32 v227, 0xffff0000, v227
	v_pk_fma_f32 v[42:43], v[42:43], v[226:227], v[132:133]
	s_nop 0
	v_bfe_u32 v220, v40, 16, 1
	v_add3_u32 v40, v40, v220, s33
	v_bfe_u32 v220, v41, 16, 1
	v_add3_u32 v41, v41, v220, s33
	v_bfe_u32 v220, v42, 16, 1
	v_add3_u32 v42, v42, v220, s33
	v_bfe_u32 v220, v43, 16, 1
	v_add3_u32 v43, v43, v220, s33
	v_perm_b32 v40, v41, v40, s96
	v_perm_b32 v41, v43, v42, s96
	global_store_dwordx2 v[214:215], v[40:41], off offset:32
	s_waitcnt vmcnt(15)
	v_lshlrev_b32_e32 v220, 16, v246
	v_and_b32_e32 v221, 0xffff0000, v246
	v_pk_fma_f32 v[36:37], v[36:37], v[220:221], v[156:157]
	v_lshlrev_b32_e32 v246, 16, v247
	v_and_b32_e32 v247, 0xffff0000, v247
	v_pk_fma_f32 v[38:39], v[38:39], v[246:247], v[158:159]
	s_nop 0
	v_bfe_u32 v220, v36, 16, 1
	v_add3_u32 v36, v36, v220, s33
	v_bfe_u32 v220, v37, 16, 1
	v_add3_u32 v37, v37, v220, s33
	v_bfe_u32 v220, v38, 16, 1
	v_add3_u32 v38, v38, v220, s33
	v_bfe_u32 v220, v39, 16, 1
	v_add3_u32 v39, v39, v220, s33
	v_perm_b32 v36, v37, v36, s96
	v_perm_b32 v37, v39, v38, s96
	global_store_dwordx2 v[214:215], v[36:37], off offset:64
	s_waitcnt vmcnt(15)
	v_lshlrev_b32_e32 v220, 16, v248
	v_and_b32_e32 v221, 0xffff0000, v248
	v_pk_fma_f32 v[32:33], v[32:33], v[220:221], v[166:167]
	v_lshlrev_b32_e32 v248, 16, v249
	v_and_b32_e32 v249, 0xffff0000, v249
	v_pk_fma_f32 v[34:35], v[34:35], v[248:249], v[168:169]
	s_nop 0
	v_bfe_u32 v220, v32, 16, 1
	v_add3_u32 v32, v32, v220, s33
	v_bfe_u32 v220, v33, 16, 1
	v_add3_u32 v33, v33, v220, s33
	v_bfe_u32 v220, v34, 16, 1
	v_add3_u32 v34, v34, v220, s33
	v_bfe_u32 v220, v35, 16, 1
	v_add3_u32 v35, v35, v220, s33
	v_perm_b32 v32, v33, v32, s96
	v_perm_b32 v33, v35, v34, s96
	global_store_dwordx2 v[214:215], v[32:33], off offset:96
	v_add_u32_e32 v222, 0x18000, v210
	v_lshl_add_u64 v[214:215], v[222:223], 0, s[6:7]
	s_waitcnt vmcnt(11)
	v_lshlrev_b32_e32 v220, 16, v242
	v_and_b32_e32 v221, 0xffff0000, v242
	v_pk_fma_f32 v[28:29], v[28:29], v[220:221], v[182:183]
	v_lshlrev_b32_e32 v242, 16, v243
	v_and_b32_e32 v243, 0xffff0000, v243
	v_pk_fma_f32 v[30:31], v[30:31], v[242:243], v[184:185]
	s_nop 0
	v_bfe_u32 v220, v28, 16, 1
	v_add3_u32 v28, v28, v220, s33
	v_bfe_u32 v220, v29, 16, 1
	v_add3_u32 v29, v29, v220, s33
	v_bfe_u32 v220, v30, 16, 1
	v_add3_u32 v30, v30, v220, s33
	v_bfe_u32 v220, v31, 16, 1
	v_add3_u32 v31, v31, v220, s33
	v_perm_b32 v28, v29, v28, s96
	v_perm_b32 v29, v31, v30, s96
	global_store_dwordx2 v[214:215], v[28:29], off
	s_waitcnt vmcnt(11)
	v_lshlrev_b32_e32 v220, 16, v244
	v_and_b32_e32 v221, 0xffff0000, v244
	v_pk_fma_f32 v[24:25], v[24:25], v[220:221], v[186:187]
	v_lshlrev_b32_e32 v244, 16, v245
	v_and_b32_e32 v245, 0xffff0000, v245
	v_pk_fma_f32 v[26:27], v[26:27], v[244:245], v[188:189]
	s_nop 0
	v_bfe_u32 v220, v24, 16, 1
	v_add3_u32 v24, v24, v220, s33
	v_bfe_u32 v220, v25, 16, 1
	v_add3_u32 v25, v25, v220, s33
	v_bfe_u32 v220, v26, 16, 1
	v_add3_u32 v26, v26, v220, s33
	v_bfe_u32 v220, v27, 16, 1
	v_add3_u32 v27, v27, v220, s33
	v_perm_b32 v24, v25, v24, s96
	v_perm_b32 v25, v27, v26, s96
	global_store_dwordx2 v[214:215], v[24:25], off offset:32
	s_waitcnt vmcnt(11)
	v_lshlrev_b32_e32 v220, 16, v238
	v_and_b32_e32 v221, 0xffff0000, v238
	v_pk_fma_f32 v[20:21], v[20:21], v[220:221], v[190:191]
	v_lshlrev_b32_e32 v238, 16, v239
	v_and_b32_e32 v239, 0xffff0000, v239
	v_pk_fma_f32 v[22:23], v[22:23], v[238:239], v[192:193]
	s_nop 0
	v_bfe_u32 v220, v20, 16, 1
	v_add3_u32 v20, v20, v220, s33
	v_bfe_u32 v220, v21, 16, 1
	v_add3_u32 v21, v21, v220, s33
	v_bfe_u32 v220, v22, 16, 1
	v_add3_u32 v22, v22, v220, s33
	v_bfe_u32 v220, v23, 16, 1
	v_add3_u32 v23, v23, v220, s33
	v_perm_b32 v20, v21, v20, s96
	v_perm_b32 v21, v23, v22, s96
	global_store_dwordx2 v[214:215], v[20:21], off offset:64
	s_waitcnt vmcnt(11)
	v_lshlrev_b32_e32 v220, 16, v240
	v_and_b32_e32 v221, 0xffff0000, v240
	v_pk_fma_f32 v[16:17], v[16:17], v[220:221], v[194:195]
	v_lshlrev_b32_e32 v240, 16, v241
	v_and_b32_e32 v241, 0xffff0000, v241
	v_pk_fma_f32 v[18:19], v[18:19], v[240:241], v[196:197]
	s_nop 0
	v_bfe_u32 v220, v16, 16, 1
	v_add3_u32 v16, v16, v220, s33
	v_bfe_u32 v220, v17, 16, 1
	v_add3_u32 v17, v17, v220, s33
	v_bfe_u32 v220, v18, 16, 1
	v_add3_u32 v18, v18, v220, s33
	v_bfe_u32 v220, v19, 16, 1
	v_add3_u32 v19, v19, v220, s33
	v_perm_b32 v16, v17, v16, s96
	v_perm_b32 v17, v19, v18, s96
	global_store_dwordx2 v[214:215], v[16:17], off offset:96
	v_add_u32_e32 v222, 0x20000, v210
	v_lshl_add_u64 v[214:215], v[222:223], 0, s[6:7]
	s_waitcnt vmcnt(11)
	v_lshlrev_b32_e32 v220, 16, v234
	v_and_b32_e32 v221, 0xffff0000, v234
	v_pk_fma_f32 v[12:13], v[12:13], v[220:221], v[76:77]
	v_lshlrev_b32_e32 v234, 16, v235
	v_and_b32_e32 v235, 0xffff0000, v235
	v_pk_fma_f32 v[14:15], v[14:15], v[234:235], v[78:79]
	s_nop 0
	v_bfe_u32 v220, v12, 16, 1
	v_add3_u32 v12, v12, v220, s33
	v_bfe_u32 v220, v13, 16, 1
	v_add3_u32 v13, v13, v220, s33
	v_bfe_u32 v220, v14, 16, 1
	v_add3_u32 v14, v14, v220, s33
	v_bfe_u32 v220, v15, 16, 1
	v_add3_u32 v15, v15, v220, s33
	v_perm_b32 v12, v13, v12, s96
	v_perm_b32 v13, v15, v14, s96
	global_store_dwordx2 v[214:215], v[12:13], off
	s_waitcnt vmcnt(11)
	v_lshlrev_b32_e32 v220, 16, v236
	v_and_b32_e32 v221, 0xffff0000, v236
	v_pk_fma_f32 v[8:9], v[8:9], v[220:221], v[106:107]
	v_lshlrev_b32_e32 v236, 16, v237
	v_and_b32_e32 v237, 0xffff0000, v237
	v_pk_fma_f32 v[10:11], v[10:11], v[236:237], v[108:109]
	s_nop 0
	v_bfe_u32 v220, v8, 16, 1
	v_add3_u32 v8, v8, v220, s33
	v_bfe_u32 v220, v9, 16, 1
	v_add3_u32 v9, v9, v220, s33
	v_bfe_u32 v220, v10, 16, 1
	v_add3_u32 v10, v10, v220, s33
	v_bfe_u32 v220, v11, 16, 1
	v_add3_u32 v11, v11, v220, s33
	v_perm_b32 v8, v9, v8, s96
	v_perm_b32 v9, v11, v10, s96
	global_store_dwordx2 v[214:215], v[8:9], off offset:32
	s_waitcnt vmcnt(11)
	v_lshlrev_b32_e32 v220, 16, v230
	v_and_b32_e32 v221, 0xffff0000, v230
	v_pk_fma_f32 v[4:5], v[4:5], v[220:221], v[110:111]
	v_lshlrev_b32_e32 v230, 16, v231
	v_and_b32_e32 v231, 0xffff0000, v231
	v_pk_fma_f32 v[6:7], v[6:7], v[230:231], v[112:113]
	s_nop 0
	v_bfe_u32 v220, v4, 16, 1
	v_add3_u32 v4, v4, v220, s33
	v_bfe_u32 v220, v5, 16, 1
	v_add3_u32 v5, v5, v220, s33
	v_bfe_u32 v220, v6, 16, 1
	v_add3_u32 v6, v6, v220, s33
	v_bfe_u32 v220, v7, 16, 1
	v_add3_u32 v7, v7, v220, s33
	v_perm_b32 v4, v5, v4, s96
	v_perm_b32 v5, v7, v6, s96
	global_store_dwordx2 v[214:215], v[4:5], off offset:64
	s_waitcnt vmcnt(11)
	v_lshlrev_b32_e32 v220, 16, v232
	v_and_b32_e32 v221, 0xffff0000, v232
	v_pk_fma_f32 v[0:1], v[0:1], v[220:221], v[122:123]
	v_lshlrev_b32_e32 v232, 16, v233
	v_and_b32_e32 v233, 0xffff0000, v233
	v_pk_fma_f32 v[2:3], v[2:3], v[232:233], v[124:125]
	s_nop 0
	v_bfe_u32 v220, v0, 16, 1
	v_add3_u32 v0, v0, v220, s33
	v_bfe_u32 v220, v1, 16, 1
	v_add3_u32 v1, v1, v220, s33
	v_bfe_u32 v220, v2, 16, 1
	v_add3_u32 v2, v2, v220, s33
	v_bfe_u32 v220, v3, 16, 1
	v_add3_u32 v3, v3, v220, s33
	v_perm_b32 v0, v1, v0, s96
	v_perm_b32 v1, v3, v2, s96
	global_store_dwordx2 v[214:215], v[0:1], off offset:96
	s_mov_b32 s35, 0
	s_movk_i32 s8, 0x50
	s_movk_i32 s10, 0x3200
	s_mov_b64 s[12:13], 0x2800
